# GEMM K-loop MFMA loop-nest order Nmnb, k innermost
# speedup vs baseline: 1.0015x; 1.0015x over previous
; #define PG8_STAGE(bufoff, gbase, voff) do { _Pragma("unroll") for (int _i = 0; _i < 2; ++_i) \
;         __builtin_amdgcn_global_load_lds((const unsigned*)((const char*)(gbase) + (voff)[_i]), (PG8_LAS unsigned*)(lds + (bufoff) + ldsw + _i * 8192), 16, 0, 0); } while (0)
; #define PG8_LDA(dst, b, h) do { _Pragma("unroll") for (int m = 0; m < 4; ++m) _Pragma("unroll") for (int k = 0; k < 2; ++k) dst[m][k] = *(const PG8_LAS bf16x8*)(lds + PG8_SA(b, h) + aoff + m * 2048 + k * 1024); } while (0)
; #define PG8_LDB(dst, b, h) do { _Pragma("unroll") for (int n = 0; n < 2; ++n) _Pragma("unroll") for (int k = 0; k < 2; ++k) dst[n][k] = *(const PG8_LAS bf16x8*)(lds + PG8_SB(b, h) + boff + n * 2048 + k * 1024); } while (0)
; #define PG8_MMA(ai, bj, At, Bt) do { __builtin_amdgcn_s_setprio(1); _Pragma("unroll") for (int m = 0; m < 4; ++m) _Pragma("unroll") for (int n = 0; n < 2; ++n) _Pragma("unroll") for (int k = 0; k < 2; ++k) \
;         acc[ai][bj][m][n] = __builtin_amdgcn_mfma_f32_16x16x32_bf16(Bt[n][k], At[m][k], acc[ai][bj][m][n], 0, 0, 0); __builtin_amdgcn_s_setprio(0); } while (0)
; #define PG8_WAIT_V(n) asm volatile("s_waitcnt vmcnt(" #n ")" ::: "memory")
; #define PG8_BAR __builtin_amdgcn_s_barrier()
; template <class Epi, class Sched, bool ALIGN_EPI = false, bool SP2 = false>
; __device__ __forceinline__ void gemm_phase(PG8_LAS unsigned char* lds, const Gemm g, const Sched& S, const Epi& E) {
;     ...
;         for (int t = 0; t < nt; t += 2) {
;             const bool last = (t == nt - 2);
;             const char* a1 = cA + (size_t)(t + 1) * kstep;
;             const char* a2 = last ? nA : cA + (size_t)(t + 2) * kstep; const char* b2 = last ? nB : cB + (size_t)(t + 2) * kstep;
;             const char* a3 = a2 + kstep; const char* b3 = b2 + kstep;
;             if (last && has_next) S.a_ready(nxt);
;             if constexpr (SP2) {
;             PG8_LDB(B0, 0, 0); PG8_LDB(B1, 0, 1); PG8_SCHED; PG8_LDA(At, 0, 0); PG8_STAGE(PG8_SA(1, 1), a1 + hstep, voffA);
;             PG8_WAIT_V(8); PG8_WAIT_L(0); PG8_BAR; PG8_MMA(0, 0, At, B0); PG8_MMA(0, 1, At, B1); PG8_BAR; PG8_SCHED;
;             PG8_LDA(At, 0, 1); PG8_STAGE(PG8_SB(0, 0), b2, voffB); PG8_STAGE(PG8_SB(0, 1), b2 + hstep, voffB); PG8_STAGE(PG8_SA(0, 0), a2, voffA);
;             PG8_WAIT_V(8); PG8_WAIT_L(0); PG8_BAR; PG8_MMA(1, 0, At, B0); PG8_MMA(1, 1, At, B1); PG8_BAR; PG8_SCHED;
.LBB0_132:
	s_add_u32 s18, s46, 0xfffc0080
	s_addc_u32 s38, s47, -1
	s_add_i32 s39, 0, 0x10000
	s_cmp_eq_u32 s85, 12
	s_cselect_b32 s81, s33, s38
	s_cselect_b32 s80, s73, s18
	v_add_u32_e32 v0, s39, v176
	s_cselect_b32 s45, s75, s84
	s_cselect_b32 s44, s82, s83
	s_add_i32 s18, 0, 0x14000
	ds_read_b128 v[144:147], v0
	ds_read_b128 v[148:151], v0 offset:1024
	ds_read_b128 v[152:155], v0 offset:2048
	ds_read_b128 v[156:159], v0 offset:3072
	v_add_u32_e32 v0, s18, v176
	ds_read_b128 v[160:163], v0
	ds_read_b128 v[164:167], v0 offset:1024
	ds_read_b128 v[168:171], v0 offset:2048
	ds_read_b128 v[172:175], v0 offset:3072
	v_lshl_add_u64 v[218:219], s[46:47], 0, v[140:141]
	s_add_i32 m0, s92, 0xc000
	ds_read_b128 v[180:183], v178
	ds_read_b128 v[184:187], v178 offset:1024
	ds_read_b128 v[188:191], v178 offset:2048
	ds_read_b128 v[192:195], v178 offset:3072
	ds_read_b128 v[202:205], v178 offset:4096
	ds_read_b128 v[206:209], v178 offset:5120
	ds_read_b128 v[210:213], v178 offset:6144
	ds_read_b128 v[214:217], v178 offset:7168
	global_load_lds_dwordx4 v[218:219], off
	v_lshl_add_u64 v[218:219], s[46:47], 0, v[142:143]
	s_add_i32 m0, s92, 0xe000
	s_nop 0
	global_load_lds_dwordx4 v[218:219], off
	s_waitcnt vmcnt(8)
	s_waitcnt lgkmcnt(0)
	s_barrier
	s_setprio 1
	s_waitcnt lgkmcnt(0)
	v_mfma_f32_16x16x32_bf16 v[118:121], v[144:147], v[180:183], v[118:121]
	v_mfma_f32_16x16x32_bf16 v[118:121], v[148:151], v[184:187], v[118:121]
	v_mfma_f32_16x16x32_bf16 v[126:129], v[160:163], v[180:183], v[126:129]
	v_mfma_f32_16x16x32_bf16 v[126:129], v[164:167], v[184:187], v[126:129]
	v_mfma_f32_16x16x32_bf16 v[114:117], v[152:155], v[180:183], v[114:117]
	v_mfma_f32_16x16x32_bf16 v[114:117], v[156:159], v[184:187], v[114:117]
	v_mfma_f32_16x16x32_bf16 v[122:125], v[168:171], v[180:183], v[122:125]
	v_mfma_f32_16x16x32_bf16 v[122:125], v[172:175], v[184:187], v[122:125]
	v_mfma_f32_16x16x32_bf16 v[102:105], v[144:147], v[188:191], v[102:105]
	v_mfma_f32_16x16x32_bf16 v[102:105], v[148:151], v[192:195], v[102:105]
	v_mfma_f32_16x16x32_bf16 v[110:113], v[160:163], v[188:191], v[110:113]
	v_mfma_f32_16x16x32_bf16 v[110:113], v[164:167], v[192:195], v[110:113]
	v_mfma_f32_16x16x32_bf16 v[98:101], v[152:155], v[188:191], v[98:101]
	v_mfma_f32_16x16x32_bf16 v[98:101], v[156:159], v[192:195], v[98:101]
	v_mfma_f32_16x16x32_bf16 v[106:109], v[168:171], v[188:191], v[106:109]
	v_mfma_f32_16x16x32_bf16 v[106:109], v[172:175], v[192:195], v[106:109]
	v_mfma_f32_16x16x32_bf16 v[86:89], v[144:147], v[202:205], v[86:89]
	v_mfma_f32_16x16x32_bf16 v[86:89], v[148:151], v[206:209], v[86:89]
	v_mfma_f32_16x16x32_bf16 v[94:97], v[160:163], v[202:205], v[94:97]
	v_mfma_f32_16x16x32_bf16 v[94:97], v[164:167], v[206:209], v[94:97]
	v_mfma_f32_16x16x32_bf16 v[82:85], v[152:155], v[202:205], v[82:85]
	v_mfma_f32_16x16x32_bf16 v[82:85], v[156:159], v[206:209], v[82:85]
	v_mfma_f32_16x16x32_bf16 v[90:93], v[168:171], v[202:205], v[90:93]
	v_mfma_f32_16x16x32_bf16 v[90:93], v[172:175], v[206:209], v[90:93]
	v_mfma_f32_16x16x32_bf16 v[70:73], v[144:147], v[210:213], v[70:73]
	v_mfma_f32_16x16x32_bf16 v[70:73], v[148:151], v[214:217], v[70:73]
	v_mfma_f32_16x16x32_bf16 v[78:81], v[160:163], v[210:213], v[78:81]
	v_mfma_f32_16x16x32_bf16 v[78:81], v[164:167], v[214:217], v[78:81]
	v_mfma_f32_16x16x32_bf16 v[66:69], v[152:155], v[210:213], v[66:69]
	v_mfma_f32_16x16x32_bf16 v[66:69], v[156:159], v[214:217], v[66:69]
	v_mfma_f32_16x16x32_bf16 v[74:77], v[168:171], v[210:213], v[74:77]
	v_mfma_f32_16x16x32_bf16 v[74:77], v[172:175], v[214:217], v[74:77]
	s_setprio 0
	s_barrier
	s_add_i32 s38, s39, s91
	v_lshl_add_u64 v[218:219], s[44:45], 0, v[134:135]
	s_mov_b32 m0, s38
	ds_read_b128 v[180:183], v178 offset:16384
	ds_read_b128 v[184:187], v178 offset:17408
	ds_read_b128 v[188:191], v178 offset:18432
	ds_read_b128 v[192:195], v178 offset:19456
	ds_read_b128 v[202:205], v178 offset:20480
	ds_read_b128 v[206:209], v178 offset:21504
	ds_read_b128 v[210:213], v178 offset:22528
	ds_read_b128 v[214:217], v178 offset:23552
	global_load_lds_dwordx4 v[218:219], off
	s_add_i32 m0, s38, 0x2000
	s_add_u32 s38, s44, 0x40000
	v_lshl_add_u64 v[220:221], s[44:45], 0, v[130:131]
	s_addc_u32 s39, s45, 0
	s_add_i32 s18, s18, s91
	global_load_lds_dwordx4 v[220:221], off
	v_lshl_add_u64 v[222:223], s[38:39], 0, v[134:135]
	s_mov_b32 m0, s18
	v_lshl_add_u64 v[224:225], s[80:81], 0, v[132:133]
	global_load_lds_dwordx4 v[222:223], off
	v_lshl_add_u64 v[222:223], s[38:39], 0, v[130:131]
	s_add_i32 m0, s18, 0x2000
	s_nop 0
	global_load_lds_dwordx4 v[222:223], off
	v_lshl_add_u64 v[222:223], s[80:81], 0, v[136:137]
	s_mov_b32 m0, s92
	s_nop 0
	global_load_lds_dwordx4 v[222:223], off
	s_mov_b32 m0, s93
	s_nop 0
	global_load_lds_dwordx4 v[224:225], off
	s_waitcnt vmcnt(8)
	s_waitcnt lgkmcnt(0)
	s_barrier
; #define PG8_STAGE(bufoff, gbase, voff) do { _Pragma("unroll") for (int _i = 0; _i < 2; ++_i) \
;         __builtin_amdgcn_global_load_lds((const unsigned*)((const char*)(gbase) + (voff)[_i]), (PG8_LAS unsigned*)(lds + (bufoff) + ldsw + _i * 8192), 16, 0, 0); } while (0)
; #define PG8_LDA(dst, b, h) do { _Pragma("unroll") for (int m = 0; m < 4; ++m) _Pragma("unroll") for (int k = 0; k < 2; ++k) dst[m][k] = *(const PG8_LAS bf16x8*)(lds + PG8_SA(b, h) + aoff + m * 2048 + k * 1024); } while (0)
; #define PG8_LDB(dst, b, h) do { _Pragma("unroll") for (int n = 0; n < 2; ++n) _Pragma("unroll") for (int k = 0; k < 2; ++k) dst[n][k] = *(const PG8_LAS bf16x8*)(lds + PG8_SB(b, h) + boff + n * 2048 + k * 1024); } while (0)
; #define PG8_MMA(ai, bj, At, Bt) do { __builtin_amdgcn_s_setprio(1); _Pragma("unroll") for (int m = 0; m < 4; ++m) _Pragma("unroll") for (int n = 0; n < 2; ++n) _Pragma("unroll") for (int k = 0; k < 2; ++k) \
;         acc[ai][bj][m][n] = __builtin_amdgcn_mfma_f32_16x16x32_bf16(Bt[n][k], At[m][k], acc[ai][bj][m][n], 0, 0, 0); __builtin_amdgcn_s_setprio(0); } while (0)
; #define PG8_WAIT_V(n) asm volatile("s_waitcnt vmcnt(" #n ")" ::: "memory")
; #define PG8_WAIT_L(n) asm volatile("s_waitcnt lgkmcnt(" #n ")" ::: "memory")
; #define PG8_BAR __builtin_amdgcn_s_barrier()
; #define PG8_SCHED __builtin_amdgcn_sched_barrier(0)
; template <class Epi, class Sched, bool ALIGN_EPI = false, bool SP2 = false>
; __device__ __forceinline__ void gemm_phase(PG8_LAS unsigned char* lds, const Gemm g, const Sched& S, const Epi& E) {
;     ...
;             PG8_WAIT_V(8); PG8_WAIT_L(0); PG8_BAR; PG8_MMA(1, 0, At, B0); PG8_MMA(1, 1, At, B1); PG8_BAR; PG8_SCHED;
;             PG8_LDB(B0, 1, 0); PG8_LDB(B1, 1, 1); PG8_SCHED; PG8_LDA(At, 1, 0); PG8_STAGE(PG8_SA(0, 1), a2 + hstep, voffA);
;             PG8_WAIT_V(8); PG8_WAIT_L(0); PG8_BAR; PG8_MMA(0, 0, At, B0); PG8_MMA(0, 1, At, B1); PG8_BAR; PG8_SCHED;
	s_setprio 1
	s_waitcnt lgkmcnt(0)
	v_mfma_f32_16x16x32_bf16 v[54:57], v[144:147], v[180:183], v[54:57]
	v_mfma_f32_16x16x32_bf16 v[54:57], v[148:151], v[184:187], v[54:57]
	v_mfma_f32_16x16x32_bf16 v[62:65], v[160:163], v[180:183], v[62:65]
	v_mfma_f32_16x16x32_bf16 v[62:65], v[164:167], v[184:187], v[62:65]
	v_mfma_f32_16x16x32_bf16 v[50:53], v[152:155], v[180:183], v[50:53]
	v_mfma_f32_16x16x32_bf16 v[50:53], v[156:159], v[184:187], v[50:53]
	v_mfma_f32_16x16x32_bf16 v[58:61], v[168:171], v[180:183], v[58:61]
	v_mfma_f32_16x16x32_bf16 v[58:61], v[172:175], v[184:187], v[58:61]
	v_mfma_f32_16x16x32_bf16 v[38:41], v[144:147], v[188:191], v[38:41]
	v_mfma_f32_16x16x32_bf16 v[38:41], v[148:151], v[192:195], v[38:41]
	v_mfma_f32_16x16x32_bf16 v[46:49], v[160:163], v[188:191], v[46:49]
	v_mfma_f32_16x16x32_bf16 v[46:49], v[164:167], v[192:195], v[46:49]
	v_mfma_f32_16x16x32_bf16 v[34:37], v[152:155], v[188:191], v[34:37]
	v_mfma_f32_16x16x32_bf16 v[34:37], v[156:159], v[192:195], v[34:37]
	v_mfma_f32_16x16x32_bf16 v[42:45], v[168:171], v[188:191], v[42:45]
	v_mfma_f32_16x16x32_bf16 v[42:45], v[172:175], v[192:195], v[42:45]
	v_mfma_f32_16x16x32_bf16 v[22:25], v[144:147], v[202:205], v[22:25]
	v_mfma_f32_16x16x32_bf16 v[22:25], v[148:151], v[206:209], v[22:25]
	v_mfma_f32_16x16x32_bf16 v[30:33], v[160:163], v[202:205], v[30:33]
	v_mfma_f32_16x16x32_bf16 v[30:33], v[164:167], v[206:209], v[30:33]
	v_mfma_f32_16x16x32_bf16 v[18:21], v[152:155], v[202:205], v[18:21]
	v_mfma_f32_16x16x32_bf16 v[18:21], v[156:159], v[206:209], v[18:21]
	v_mfma_f32_16x16x32_bf16 v[26:29], v[168:171], v[202:205], v[26:29]
	v_mfma_f32_16x16x32_bf16 v[26:29], v[172:175], v[206:209], v[26:29]
	v_mfma_f32_16x16x32_bf16 v[6:9], v[144:147], v[210:213], v[6:9]
	v_mfma_f32_16x16x32_bf16 v[6:9], v[148:151], v[214:217], v[6:9]
	v_mfma_f32_16x16x32_bf16 v[10:13], v[160:163], v[210:213], v[10:13]
	v_mfma_f32_16x16x32_bf16 v[10:13], v[164:167], v[214:217], v[10:13]
	v_mfma_f32_16x16x32_bf16 v[2:5], v[152:155], v[210:213], v[2:5]
	v_mfma_f32_16x16x32_bf16 v[2:5], v[156:159], v[214:217], v[2:5]
	v_mfma_f32_16x16x32_bf16 v[14:17], v[168:171], v[210:213], v[14:17]
	v_mfma_f32_16x16x32_bf16 v[14:17], v[172:175], v[214:217], v[14:17]
	s_setprio 0
	s_barrier
	s_add_i32 s18, 0, 0x18000
	v_add_u32_e32 v0, s18, v176
	s_add_i32 vcc_lo, 0, 0x1c000
	ds_read_b128 v[144:147], v0
	ds_read_b128 v[148:151], v0 offset:1024
	ds_read_b128 v[152:155], v0 offset:2048
	ds_read_b128 v[156:159], v0 offset:3072
	v_add_u32_e32 v0, vcc_lo, v176
	ds_read_b128 v[160:163], v0
	ds_read_b128 v[164:167], v0 offset:1024
	ds_read_b128 v[168:171], v0 offset:2048
	ds_read_b128 v[172:175], v0 offset:3072
	s_add_u32 s38, s80, 0x40000
	s_addc_u32 s39, s81, 0
	s_mov_b32 m0, s94
	v_lshl_add_u64 v[226:227], s[38:39], 0, v[136:137]
	ds_read_b128 v[180:183], v178 offset:32768
	ds_read_b128 v[184:187], v178 offset:33792
	ds_read_b128 v[188:191], v178 offset:34816
	ds_read_b128 v[192:195], v178 offset:35840
	ds_read_b128 v[202:205], v178 offset:36864
	ds_read_b128 v[206:209], v178 offset:37888
	ds_read_b128 v[210:213], v178 offset:38912
	ds_read_b128 v[214:217], v178 offset:39936
	global_load_lds_dwordx4 v[226:227], off
	v_lshl_add_u64 v[226:227], s[38:39], 0, v[132:133]
	s_mov_b32 m0, s95
	s_nop 0
	global_load_lds_dwordx4 v[226:227], off
	s_waitcnt vmcnt(8)
	s_waitcnt lgkmcnt(0)
	s_barrier
	s_setprio 1
	s_waitcnt lgkmcnt(0)
	v_mfma_f32_16x16x32_bf16 v[118:121], v[144:147], v[180:183], v[118:121]
	v_mfma_f32_16x16x32_bf16 v[118:121], v[148:151], v[184:187], v[118:121]
	v_mfma_f32_16x16x32_bf16 v[126:129], v[160:163], v[180:183], v[126:129]
	v_mfma_f32_16x16x32_bf16 v[126:129], v[164:167], v[184:187], v[126:129]
	v_mfma_f32_16x16x32_bf16 v[114:117], v[152:155], v[180:183], v[114:117]
	v_mfma_f32_16x16x32_bf16 v[114:117], v[156:159], v[184:187], v[114:117]
	v_mfma_f32_16x16x32_bf16 v[122:125], v[168:171], v[180:183], v[122:125]
	v_mfma_f32_16x16x32_bf16 v[122:125], v[172:175], v[184:187], v[122:125]
	v_mfma_f32_16x16x32_bf16 v[102:105], v[144:147], v[188:191], v[102:105]
	v_mfma_f32_16x16x32_bf16 v[102:105], v[148:151], v[192:195], v[102:105]
	v_mfma_f32_16x16x32_bf16 v[110:113], v[160:163], v[188:191], v[110:113]
	v_mfma_f32_16x16x32_bf16 v[110:113], v[164:167], v[192:195], v[110:113]
	v_mfma_f32_16x16x32_bf16 v[98:101], v[152:155], v[188:191], v[98:101]
	v_mfma_f32_16x16x32_bf16 v[98:101], v[156:159], v[192:195], v[98:101]
	v_mfma_f32_16x16x32_bf16 v[106:109], v[168:171], v[188:191], v[106:109]
	v_mfma_f32_16x16x32_bf16 v[106:109], v[172:175], v[192:195], v[106:109]
	v_mfma_f32_16x16x32_bf16 v[86:89], v[144:147], v[202:205], v[86:89]
	v_mfma_f32_16x16x32_bf16 v[86:89], v[148:151], v[206:209], v[86:89]
	v_mfma_f32_16x16x32_bf16 v[94:97], v[160:163], v[202:205], v[94:97]
	v_mfma_f32_16x16x32_bf16 v[94:97], v[164:167], v[206:209], v[94:97]
	v_mfma_f32_16x16x32_bf16 v[82:85], v[152:155], v[202:205], v[82:85]
	v_mfma_f32_16x16x32_bf16 v[82:85], v[156:159], v[206:209], v[82:85]
	v_mfma_f32_16x16x32_bf16 v[90:93], v[168:171], v[202:205], v[90:93]
	v_mfma_f32_16x16x32_bf16 v[90:93], v[172:175], v[206:209], v[90:93]
	v_mfma_f32_16x16x32_bf16 v[70:73], v[144:147], v[210:213], v[70:73]
	v_mfma_f32_16x16x32_bf16 v[70:73], v[148:151], v[214:217], v[70:73]
	v_mfma_f32_16x16x32_bf16 v[78:81], v[160:163], v[210:213], v[78:81]
	v_mfma_f32_16x16x32_bf16 v[78:81], v[164:167], v[214:217], v[78:81]
	v_mfma_f32_16x16x32_bf16 v[66:69], v[152:155], v[210:213], v[66:69]
	v_mfma_f32_16x16x32_bf16 v[66:69], v[156:159], v[214:217], v[66:69]
	v_mfma_f32_16x16x32_bf16 v[74:77], v[168:171], v[210:213], v[74:77]
	v_mfma_f32_16x16x32_bf16 v[74:77], v[172:175], v[214:217], v[74:77]
	s_setprio 0
	s_barrier
; #define PG8_STAGE(bufoff, gbase, voff) do { _Pragma("unroll") for (int _i = 0; _i < 2; ++_i) \
;         __builtin_amdgcn_global_load_lds((const unsigned*)((const char*)(gbase) + (voff)[_i]), (PG8_LAS unsigned*)(lds + (bufoff) + ldsw + _i * 8192), 16, 0, 0); } while (0)
; #define PG8_LDA(dst, b, h) do { _Pragma("unroll") for (int m = 0; m < 4; ++m) _Pragma("unroll") for (int k = 0; k < 2; ++k) dst[m][k] = *(const PG8_LAS bf16x8*)(lds + PG8_SA(b, h) + aoff + m * 2048 + k * 1024); } while (0)
; #define PG8_MMA(ai, bj, At, Bt) do { __builtin_amdgcn_s_setprio(1); _Pragma("unroll") for (int m = 0; m < 4; ++m) _Pragma("unroll") for (int n = 0; n < 2; ++n) _Pragma("unroll") for (int k = 0; k < 2; ++k) \
;         acc[ai][bj][m][n] = __builtin_amdgcn_mfma_f32_16x16x32_bf16(Bt[n][k], At[m][k], acc[ai][bj][m][n], 0, 0, 0); __builtin_amdgcn_s_setprio(0); } while (0)
; #define PG8_WAIT_V(n) asm volatile("s_waitcnt vmcnt(" #n ")" ::: "memory")
; #define PG8_WAIT_L(n) asm volatile("s_waitcnt lgkmcnt(" #n ")" ::: "memory")
; #define PG8_BAR __builtin_amdgcn_s_barrier()
; #define PG8_SCHED __builtin_amdgcn_sched_barrier(0)
; template <class Epi, class Sched, bool ALIGN_EPI = false, bool SP2 = false>
; __device__ __forceinline__ void gemm_phase(PG8_LAS unsigned char* lds, const Gemm g, const Sched& S, const Epi& E) {
;     ...
;             PG8_LDA(At, 1, 1); PG8_STAGE(PG8_SB(1, 0), b3, voffB); PG8_STAGE(PG8_SB(1, 1), b3 + hstep, voffB); PG8_STAGE(PG8_SA(1, 0), a3, voffA);
;             PG8_WAIT_V(8); PG8_WAIT_L(0); PG8_BAR; PG8_MMA(1, 0, At, B0); PG8_MMA(1, 1, At, B1); PG8_BAR; PG8_SCHED;
;     ...
;         if constexpr (ALIGN_EPI) { if (wr == 0) PG8_BAR; }
	s_add_i32 s18, s18, s91
	v_lshl_add_u64 v[218:219], v[218:219], 0, s[30:31]
	s_mov_b32 m0, s18
	ds_read_b128 v[180:183], v178 offset:49152
	ds_read_b128 v[184:187], v178 offset:50176
	ds_read_b128 v[188:191], v178 offset:51200
	ds_read_b128 v[192:195], v178 offset:52224
	ds_read_b128 v[202:205], v178 offset:53248
	ds_read_b128 v[206:209], v178 offset:54272
	ds_read_b128 v[210:213], v178 offset:55296
	ds_read_b128 v[214:217], v178 offset:56320
	global_load_lds_dwordx4 v[218:219], off
	s_add_i32 m0, s18, 0x2000
	s_add_u32 s38, s44, 0x40080
	v_lshl_add_u64 v[218:219], v[220:221], 0, s[30:31]
	s_addc_u32 s39, s45, 0
	s_add_i32 s18, vcc_lo, s91
	global_load_lds_dwordx4 v[218:219], off
	v_lshl_add_u64 v[218:219], s[38:39], 0, v[134:135]
	s_mov_b32 m0, s18
	s_nop 0
	global_load_lds_dwordx4 v[218:219], off
	v_lshl_add_u64 v[218:219], s[38:39], 0, v[130:131]
	s_add_i32 m0, s18, 0x2000
	s_nop 0
	global_load_lds_dwordx4 v[218:219], off
	v_lshl_add_u64 v[218:219], v[222:223], 0, s[30:31]
	s_mov_b32 m0, s7
	s_nop 0
	global_load_lds_dwordx4 v[218:219], off
	v_lshl_add_u64 v[218:219], v[224:225], 0, s[30:31]
	s_mov_b32 m0, s96
	s_nop 0
	global_load_lds_dwordx4 v[218:219], off
	s_waitcnt vmcnt(8)
	s_waitcnt lgkmcnt(0)
	s_barrier
	s_setprio 1
	s_waitcnt lgkmcnt(0)
	v_mfma_f32_16x16x32_bf16 v[54:57], v[144:147], v[180:183], v[54:57]
	v_mfma_f32_16x16x32_bf16 v[54:57], v[148:151], v[184:187], v[54:57]
	v_mfma_f32_16x16x32_bf16 v[62:65], v[160:163], v[180:183], v[62:65]
	v_mfma_f32_16x16x32_bf16 v[62:65], v[164:167], v[184:187], v[62:65]
	v_mfma_f32_16x16x32_bf16 v[50:53], v[152:155], v[180:183], v[50:53]
	v_mfma_f32_16x16x32_bf16 v[50:53], v[156:159], v[184:187], v[50:53]
	v_mfma_f32_16x16x32_bf16 v[58:61], v[168:171], v[180:183], v[58:61]
	v_mfma_f32_16x16x32_bf16 v[58:61], v[172:175], v[184:187], v[58:61]
	v_mfma_f32_16x16x32_bf16 v[38:41], v[144:147], v[188:191], v[38:41]
	v_mfma_f32_16x16x32_bf16 v[38:41], v[148:151], v[192:195], v[38:41]
	v_mfma_f32_16x16x32_bf16 v[46:49], v[160:163], v[188:191], v[46:49]
	v_mfma_f32_16x16x32_bf16 v[46:49], v[164:167], v[192:195], v[46:49]
	v_mfma_f32_16x16x32_bf16 v[34:37], v[152:155], v[188:191], v[34:37]
	v_mfma_f32_16x16x32_bf16 v[34:37], v[156:159], v[192:195], v[34:37]
	v_mfma_f32_16x16x32_bf16 v[42:45], v[168:171], v[188:191], v[42:45]
	v_mfma_f32_16x16x32_bf16 v[42:45], v[172:175], v[192:195], v[42:45]
	v_mfma_f32_16x16x32_bf16 v[22:25], v[144:147], v[202:205], v[22:25]
	v_mfma_f32_16x16x32_bf16 v[22:25], v[148:151], v[206:209], v[22:25]
	v_mfma_f32_16x16x32_bf16 v[30:33], v[160:163], v[202:205], v[30:33]
	v_mfma_f32_16x16x32_bf16 v[30:33], v[164:167], v[206:209], v[30:33]
	v_mfma_f32_16x16x32_bf16 v[18:21], v[152:155], v[202:205], v[18:21]
	v_mfma_f32_16x16x32_bf16 v[18:21], v[156:159], v[206:209], v[18:21]
	v_mfma_f32_16x16x32_bf16 v[26:29], v[168:171], v[202:205], v[26:29]
	v_mfma_f32_16x16x32_bf16 v[26:29], v[172:175], v[206:209], v[26:29]
	v_mfma_f32_16x16x32_bf16 v[6:9], v[144:147], v[210:213], v[6:9]
	v_mfma_f32_16x16x32_bf16 v[6:9], v[148:151], v[214:217], v[6:9]
	v_mfma_f32_16x16x32_bf16 v[10:13], v[160:163], v[210:213], v[10:13]
	v_mfma_f32_16x16x32_bf16 v[10:13], v[164:167], v[214:217], v[10:13]
	v_mfma_f32_16x16x32_bf16 v[2:5], v[152:155], v[210:213], v[2:5]
	v_mfma_f32_16x16x32_bf16 v[2:5], v[156:159], v[214:217], v[2:5]
	v_mfma_f32_16x16x32_bf16 v[14:17], v[168:171], v[210:213], v[14:17]
	v_mfma_f32_16x16x32_bf16 v[14:17], v[172:175], v[214:217], v[14:17]
	s_setprio 0
	s_barrier
	s_add_i32 s85, s85, 2
	s_add_u32 s46, s46, 0x100
	s_addc_u32 s47, s47, 0
	s_add_u32 s83, s83, 0x100
	s_addc_u32 s84, s84, 0
	s_cmp_gt_u32 s85, 13
	s_cbranch_scc0 .LBB0_132
	s_and_b64 vcc, exec, s[10:11]
	s_cbranch_vccz .LBB0_135
	s_barrier

; #define PG8_STAGE(bufoff, gbase, voff) do { _Pragma("unroll") for (int _i = 0; _i < 2; ++_i) \
;         __builtin_amdgcn_global_load_lds((const unsigned*)((const char*)(gbase) + (voff)[_i]), (PG8_LAS unsigned*)(lds + (bufoff) + ldsw + _i * 8192), 16, 0, 0); } while (0)
; #define PG8_LDA(dst, b, h) do { _Pragma("unroll") for (int m = 0; m < 4; ++m) _Pragma("unroll") for (int k = 0; k < 2; ++k) dst[m][k] = *(const PG8_LAS bf16x8*)(lds + PG8_SA(b, h) + aoff + m * 2048 + k * 1024); } while (0)
; #define PG8_LDB(dst, b, h) do { _Pragma("unroll") for (int n = 0; n < 2; ++n) _Pragma("unroll") for (int k = 0; k < 2; ++k) dst[n][k] = *(const PG8_LAS bf16x8*)(lds + PG8_SB(b, h) + boff + n * 2048 + k * 1024); } while (0)
; #define PG8_MMA(ai, bj, At, Bt) do { __builtin_amdgcn_s_setprio(1); _Pragma("unroll") for (int m = 0; m < 4; ++m) _Pragma("unroll") for (int n = 0; n < 2; ++n) _Pragma("unroll") for (int k = 0; k < 2; ++k) \
;         acc[ai][bj][m][n] = __builtin_amdgcn_mfma_f32_16x16x32_bf16(Bt[n][k], At[m][k], acc[ai][bj][m][n], 0, 0, 0); __builtin_amdgcn_s_setprio(0); } while (0)
; #define PG8_WAIT_V(n) asm volatile("s_waitcnt vmcnt(" #n ")" ::: "memory")
; #define PG8_BAR __builtin_amdgcn_s_barrier()
; template <class Epi, class Sched, bool ALIGN_EPI = false, bool SP2 = false>
; __device__ __forceinline__ void gemm_phase(PG8_LAS unsigned char* lds, const Gemm g, const Sched& S, const Epi& E) {
;     ...
;         for (int t = 0; t < nt; t += 2) {
;             const bool last = (t == nt - 2);
;             const char* a1 = cA + (size_t)(t + 1) * kstep;
;             const char* a2 = last ? nA : cA + (size_t)(t + 2) * kstep; const char* b2 = last ? nB : cB + (size_t)(t + 2) * kstep;
;             const char* a3 = a2 + kstep; const char* b3 = b2 + kstep;
;             if (last && has_next) S.a_ready(nxt);
;             if constexpr (SP2) {
;             PG8_LDB(B0, 0, 0); PG8_LDB(B1, 0, 1); PG8_SCHED; PG8_LDA(At, 0, 0); PG8_STAGE(PG8_SA(1, 1), a1 + hstep, voffA);
;             PG8_WAIT_V(8); PG8_WAIT_L(0); PG8_BAR; PG8_MMA(0, 0, At, B0); PG8_MMA(0, 1, At, B1); PG8_BAR; PG8_SCHED;
;             PG8_LDA(At, 0, 1); PG8_STAGE(PG8_SB(0, 0), b2, voffB); PG8_STAGE(PG8_SB(0, 1), b2 + hstep, voffB); PG8_STAGE(PG8_SA(0, 0), a2, voffA);
;             PG8_WAIT_V(8); PG8_WAIT_L(0); PG8_BAR; PG8_MMA(1, 0, At, B0); PG8_MMA(1, 1, At, B1); PG8_BAR; PG8_SCHED;
.LBB0_220:
	s_add_u32 s18, s60, 0xfffc0080
	s_addc_u32 s38, s61, -1
	s_add_i32 s39, 0, 0x10000
	s_cmp_eq_u32 s82, 12
	s_cselect_b32 s65, s47, s38
	s_cselect_b32 s64, s78, s18
	v_add_u32_e32 v145, s39, v141
	s_cselect_b32 s57, s49, s81
	s_cselect_b32 s56, s79, s80
	s_add_i32 s18, 0, 0x14000
	ds_read_b128 v[146:149], v145
	ds_read_b128 v[150:153], v145 offset:1024
	ds_read_b128 v[154:157], v145 offset:2048
	ds_read_b128 v[158:161], v145 offset:3072
	v_add_u32_e32 v145, s18, v141
	ds_read_b128 v[162:165], v145
	ds_read_b128 v[166:169], v145 offset:1024
	ds_read_b128 v[170:173], v145 offset:2048
	ds_read_b128 v[174:177], v145 offset:3072
	v_lshl_add_u64 v[194:195], s[60:61], 0, v[136:137]
	s_add_i32 m0, s29, 0xc000
	ds_read_b128 v[178:181], v144
	ds_read_b128 v[182:185], v144 offset:1024
	ds_read_b128 v[186:189], v144 offset:2048
	ds_read_b128 v[190:193], v144 offset:3072
	ds_read_b128 v[202:205], v144 offset:4096
	ds_read_b128 v[206:209], v144 offset:5120
	ds_read_b128 v[210:213], v144 offset:6144
	ds_read_b128 v[214:217], v144 offset:7168
	global_load_lds_dwordx4 v[194:195], off
	v_lshl_add_u64 v[194:195], s[60:61], 0, v[138:139]
	s_add_i32 m0, s29, 0xe000
	s_nop 0
	global_load_lds_dwordx4 v[194:195], off
	s_waitcnt vmcnt(8)
	s_waitcnt lgkmcnt(0)
	s_barrier
	s_setprio 1
	s_waitcnt lgkmcnt(0)
	v_mfma_f32_16x16x32_bf16 v[114:117], v[146:149], v[178:181], v[114:117]
	v_mfma_f32_16x16x32_bf16 v[114:117], v[150:153], v[182:185], v[114:117]
	v_mfma_f32_16x16x32_bf16 v[122:125], v[162:165], v[178:181], v[122:125]
	v_mfma_f32_16x16x32_bf16 v[122:125], v[166:169], v[182:185], v[122:125]
	v_mfma_f32_16x16x32_bf16 v[118:121], v[154:157], v[178:181], v[118:121]
	v_mfma_f32_16x16x32_bf16 v[118:121], v[158:161], v[182:185], v[118:121]
	v_mfma_f32_16x16x32_bf16 v[126:129], v[170:173], v[178:181], v[126:129]
	v_mfma_f32_16x16x32_bf16 v[126:129], v[174:177], v[182:185], v[126:129]
	v_mfma_f32_16x16x32_bf16 v[98:101], v[146:149], v[186:189], v[98:101]
	v_mfma_f32_16x16x32_bf16 v[98:101], v[150:153], v[190:193], v[98:101]
	v_mfma_f32_16x16x32_bf16 v[106:109], v[162:165], v[186:189], v[106:109]
	v_mfma_f32_16x16x32_bf16 v[106:109], v[166:169], v[190:193], v[106:109]
	v_mfma_f32_16x16x32_bf16 v[102:105], v[154:157], v[186:189], v[102:105]
	v_mfma_f32_16x16x32_bf16 v[102:105], v[158:161], v[190:193], v[102:105]
	v_mfma_f32_16x16x32_bf16 v[110:113], v[170:173], v[186:189], v[110:113]
	v_mfma_f32_16x16x32_bf16 v[110:113], v[174:177], v[190:193], v[110:113]
	v_mfma_f32_16x16x32_bf16 v[82:85], v[146:149], v[202:205], v[82:85]
	v_mfma_f32_16x16x32_bf16 v[82:85], v[150:153], v[206:209], v[82:85]
	v_mfma_f32_16x16x32_bf16 v[90:93], v[162:165], v[202:205], v[90:93]
	v_mfma_f32_16x16x32_bf16 v[90:93], v[166:169], v[206:209], v[90:93]
	v_mfma_f32_16x16x32_bf16 v[86:89], v[154:157], v[202:205], v[86:89]
	v_mfma_f32_16x16x32_bf16 v[86:89], v[158:161], v[206:209], v[86:89]
	v_mfma_f32_16x16x32_bf16 v[94:97], v[170:173], v[202:205], v[94:97]
	v_mfma_f32_16x16x32_bf16 v[94:97], v[174:177], v[206:209], v[94:97]
	v_mfma_f32_16x16x32_bf16 v[66:69], v[146:149], v[210:213], v[66:69]
	v_mfma_f32_16x16x32_bf16 v[66:69], v[150:153], v[214:217], v[66:69]
	v_mfma_f32_16x16x32_bf16 v[74:77], v[162:165], v[210:213], v[74:77]
	v_mfma_f32_16x16x32_bf16 v[74:77], v[166:169], v[214:217], v[74:77]
	v_mfma_f32_16x16x32_bf16 v[70:73], v[154:157], v[210:213], v[70:73]
	v_mfma_f32_16x16x32_bf16 v[70:73], v[158:161], v[214:217], v[70:73]
	v_mfma_f32_16x16x32_bf16 v[78:81], v[170:173], v[210:213], v[78:81]
	v_mfma_f32_16x16x32_bf16 v[78:81], v[174:177], v[214:217], v[78:81]
	s_setprio 0
	s_barrier
	s_add_i32 s38, s39, s27
	v_lshl_add_u64 v[194:195], s[56:57], 0, v[0:1]
	s_mov_b32 m0, s38
	ds_read_b128 v[178:181], v144 offset:16384
	ds_read_b128 v[182:185], v144 offset:17408
	ds_read_b128 v[186:189], v144 offset:18432
	ds_read_b128 v[190:193], v144 offset:19456
	ds_read_b128 v[202:205], v144 offset:20480
	ds_read_b128 v[206:209], v144 offset:21504
	ds_read_b128 v[210:213], v144 offset:22528
	ds_read_b128 v[214:217], v144 offset:23552
	global_load_lds_dwordx4 v[194:195], off
	s_add_i32 m0, s38, 0x2000
	s_add_u32 s38, s56, 0x40000
	v_lshl_add_u64 v[218:219], s[56:57], 0, v[130:131]
	s_addc_u32 s39, s57, 0
	s_add_i32 s18, s18, s27
	global_load_lds_dwordx4 v[218:219], off
	v_lshl_add_u64 v[220:221], s[38:39], 0, v[0:1]
	s_mov_b32 m0, s18
	v_lshl_add_u64 v[222:223], s[64:65], 0, v[132:133]
	global_load_lds_dwordx4 v[220:221], off
	v_lshl_add_u64 v[220:221], s[38:39], 0, v[130:131]
	s_add_i32 m0, s18, 0x2000
	s_nop 0
	global_load_lds_dwordx4 v[220:221], off
	v_lshl_add_u64 v[220:221], s[64:65], 0, v[134:135]
	s_mov_b32 m0, s29
	s_nop 0
	global_load_lds_dwordx4 v[220:221], off
	s_mov_b32 m0, s33
	s_nop 0
	global_load_lds_dwordx4 v[222:223], off
	s_waitcnt vmcnt(8)
	s_waitcnt lgkmcnt(0)
	s_barrier
; #define PG8_STAGE(bufoff, gbase, voff) do { _Pragma("unroll") for (int _i = 0; _i < 2; ++_i) \
;         __builtin_amdgcn_global_load_lds((const unsigned*)((const char*)(gbase) + (voff)[_i]), (PG8_LAS unsigned*)(lds + (bufoff) + ldsw + _i * 8192), 16, 0, 0); } while (0)
; #define PG8_LDA(dst, b, h) do { _Pragma("unroll") for (int m = 0; m < 4; ++m) _Pragma("unroll") for (int k = 0; k < 2; ++k) dst[m][k] = *(const PG8_LAS bf16x8*)(lds + PG8_SA(b, h) + aoff + m * 2048 + k * 1024); } while (0)
; #define PG8_LDB(dst, b, h) do { _Pragma("unroll") for (int n = 0; n < 2; ++n) _Pragma("unroll") for (int k = 0; k < 2; ++k) dst[n][k] = *(const PG8_LAS bf16x8*)(lds + PG8_SB(b, h) + boff + n * 2048 + k * 1024); } while (0)
; #define PG8_MMA(ai, bj, At, Bt) do { __builtin_amdgcn_s_setprio(1); _Pragma("unroll") for (int m = 0; m < 4; ++m) _Pragma("unroll") for (int n = 0; n < 2; ++n) _Pragma("unroll") for (int k = 0; k < 2; ++k) \
;         acc[ai][bj][m][n] = __builtin_amdgcn_mfma_f32_16x16x32_bf16(Bt[n][k], At[m][k], acc[ai][bj][m][n], 0, 0, 0); __builtin_amdgcn_s_setprio(0); } while (0)
; #define PG8_WAIT_V(n) asm volatile("s_waitcnt vmcnt(" #n ")" ::: "memory")
; #define PG8_WAIT_L(n) asm volatile("s_waitcnt lgkmcnt(" #n ")" ::: "memory")
; #define PG8_BAR __builtin_amdgcn_s_barrier()
; #define PG8_SCHED __builtin_amdgcn_sched_barrier(0)
; template <class Epi, class Sched, bool ALIGN_EPI = false, bool SP2 = false>
; __device__ __forceinline__ void gemm_phase(PG8_LAS unsigned char* lds, const Gemm g, const Sched& S, const Epi& E) {
;     ...
;             PG8_WAIT_V(8); PG8_WAIT_L(0); PG8_BAR; PG8_MMA(1, 0, At, B0); PG8_MMA(1, 1, At, B1); PG8_BAR; PG8_SCHED;
;             PG8_LDB(B0, 1, 0); PG8_LDB(B1, 1, 1); PG8_SCHED; PG8_LDA(At, 1, 0); PG8_STAGE(PG8_SA(0, 1), a2 + hstep, voffA);
;             PG8_WAIT_V(8); PG8_WAIT_L(0); PG8_BAR; PG8_MMA(0, 0, At, B0); PG8_MMA(0, 1, At, B1); PG8_BAR; PG8_SCHED;
	s_setprio 1
	s_waitcnt lgkmcnt(0)
	v_mfma_f32_16x16x32_bf16 v[50:53], v[146:149], v[178:181], v[50:53]
	v_mfma_f32_16x16x32_bf16 v[50:53], v[150:153], v[182:185], v[50:53]
	v_mfma_f32_16x16x32_bf16 v[58:61], v[162:165], v[178:181], v[58:61]
	v_mfma_f32_16x16x32_bf16 v[58:61], v[166:169], v[182:185], v[58:61]
	v_mfma_f32_16x16x32_bf16 v[54:57], v[154:157], v[178:181], v[54:57]
	v_mfma_f32_16x16x32_bf16 v[54:57], v[158:161], v[182:185], v[54:57]
	v_mfma_f32_16x16x32_bf16 v[62:65], v[170:173], v[178:181], v[62:65]
	v_mfma_f32_16x16x32_bf16 v[62:65], v[174:177], v[182:185], v[62:65]
	v_mfma_f32_16x16x32_bf16 v[34:37], v[146:149], v[186:189], v[34:37]
	v_mfma_f32_16x16x32_bf16 v[34:37], v[150:153], v[190:193], v[34:37]
	v_mfma_f32_16x16x32_bf16 v[42:45], v[162:165], v[186:189], v[42:45]
	v_mfma_f32_16x16x32_bf16 v[42:45], v[166:169], v[190:193], v[42:45]
	v_mfma_f32_16x16x32_bf16 v[38:41], v[154:157], v[186:189], v[38:41]
	v_mfma_f32_16x16x32_bf16 v[38:41], v[158:161], v[190:193], v[38:41]
	v_mfma_f32_16x16x32_bf16 v[46:49], v[170:173], v[186:189], v[46:49]
	v_mfma_f32_16x16x32_bf16 v[46:49], v[174:177], v[190:193], v[46:49]
	v_mfma_f32_16x16x32_bf16 v[18:21], v[146:149], v[202:205], v[18:21]
	v_mfma_f32_16x16x32_bf16 v[18:21], v[150:153], v[206:209], v[18:21]
	v_mfma_f32_16x16x32_bf16 v[26:29], v[162:165], v[202:205], v[26:29]
	v_mfma_f32_16x16x32_bf16 v[26:29], v[166:169], v[206:209], v[26:29]
	v_mfma_f32_16x16x32_bf16 v[22:25], v[154:157], v[202:205], v[22:25]
	v_mfma_f32_16x16x32_bf16 v[22:25], v[158:161], v[206:209], v[22:25]
	v_mfma_f32_16x16x32_bf16 v[30:33], v[170:173], v[202:205], v[30:33]
	v_mfma_f32_16x16x32_bf16 v[30:33], v[174:177], v[206:209], v[30:33]
	v_mfma_f32_16x16x32_bf16 v[2:5], v[146:149], v[210:213], v[2:5]
	v_mfma_f32_16x16x32_bf16 v[2:5], v[150:153], v[214:217], v[2:5]
	v_mfma_f32_16x16x32_bf16 v[10:13], v[162:165], v[210:213], v[10:13]
	v_mfma_f32_16x16x32_bf16 v[10:13], v[166:169], v[214:217], v[10:13]
	v_mfma_f32_16x16x32_bf16 v[6:9], v[154:157], v[210:213], v[6:9]
	v_mfma_f32_16x16x32_bf16 v[6:9], v[158:161], v[214:217], v[6:9]
	v_mfma_f32_16x16x32_bf16 v[14:17], v[170:173], v[210:213], v[14:17]
	v_mfma_f32_16x16x32_bf16 v[14:17], v[174:177], v[214:217], v[14:17]
	s_setprio 0
	s_barrier
	s_add_i32 s18, 0, 0x18000
	v_add_u32_e32 v145, s18, v141
	s_add_i32 s83, 0, 0x1c000
	ds_read_b128 v[146:149], v145
	ds_read_b128 v[150:153], v145 offset:1024
	ds_read_b128 v[154:157], v145 offset:2048
	ds_read_b128 v[158:161], v145 offset:3072
	v_add_u32_e32 v145, s83, v141
	ds_read_b128 v[162:165], v145
	ds_read_b128 v[166:169], v145 offset:1024
	ds_read_b128 v[170:173], v145 offset:2048
	ds_read_b128 v[174:177], v145 offset:3072
	s_add_u32 s38, s64, 0x40000
	s_addc_u32 s39, s65, 0
	s_mov_b32 m0, s58
	v_lshl_add_u64 v[224:225], s[38:39], 0, v[134:135]
	ds_read_b128 v[178:181], v144 offset:32768
	ds_read_b128 v[182:185], v144 offset:33792
	ds_read_b128 v[186:189], v144 offset:34816
	ds_read_b128 v[190:193], v144 offset:35840
	ds_read_b128 v[202:205], v144 offset:36864
	ds_read_b128 v[206:209], v144 offset:37888
	ds_read_b128 v[210:213], v144 offset:38912
	ds_read_b128 v[214:217], v144 offset:39936
	global_load_lds_dwordx4 v[224:225], off
	v_lshl_add_u64 v[224:225], s[38:39], 0, v[132:133]
	s_mov_b32 m0, s69
	s_nop 0
	global_load_lds_dwordx4 v[224:225], off
	s_waitcnt vmcnt(8)
	s_waitcnt lgkmcnt(0)
	s_barrier
	s_setprio 1
	s_waitcnt lgkmcnt(0)
	v_mfma_f32_16x16x32_bf16 v[114:117], v[146:149], v[178:181], v[114:117]
	v_mfma_f32_16x16x32_bf16 v[114:117], v[150:153], v[182:185], v[114:117]
	v_mfma_f32_16x16x32_bf16 v[122:125], v[162:165], v[178:181], v[122:125]
	v_mfma_f32_16x16x32_bf16 v[122:125], v[166:169], v[182:185], v[122:125]
	v_mfma_f32_16x16x32_bf16 v[118:121], v[154:157], v[178:181], v[118:121]
	v_mfma_f32_16x16x32_bf16 v[118:121], v[158:161], v[182:185], v[118:121]
	v_mfma_f32_16x16x32_bf16 v[126:129], v[170:173], v[178:181], v[126:129]
	v_mfma_f32_16x16x32_bf16 v[126:129], v[174:177], v[182:185], v[126:129]
	v_mfma_f32_16x16x32_bf16 v[98:101], v[146:149], v[186:189], v[98:101]
	v_mfma_f32_16x16x32_bf16 v[98:101], v[150:153], v[190:193], v[98:101]
	v_mfma_f32_16x16x32_bf16 v[106:109], v[162:165], v[186:189], v[106:109]
	v_mfma_f32_16x16x32_bf16 v[106:109], v[166:169], v[190:193], v[106:109]
	v_mfma_f32_16x16x32_bf16 v[102:105], v[154:157], v[186:189], v[102:105]
	v_mfma_f32_16x16x32_bf16 v[102:105], v[158:161], v[190:193], v[102:105]
	v_mfma_f32_16x16x32_bf16 v[110:113], v[170:173], v[186:189], v[110:113]
	v_mfma_f32_16x16x32_bf16 v[110:113], v[174:177], v[190:193], v[110:113]
	v_mfma_f32_16x16x32_bf16 v[82:85], v[146:149], v[202:205], v[82:85]
	v_mfma_f32_16x16x32_bf16 v[82:85], v[150:153], v[206:209], v[82:85]
	v_mfma_f32_16x16x32_bf16 v[90:93], v[162:165], v[202:205], v[90:93]
	v_mfma_f32_16x16x32_bf16 v[90:93], v[166:169], v[206:209], v[90:93]
	v_mfma_f32_16x16x32_bf16 v[86:89], v[154:157], v[202:205], v[86:89]
	v_mfma_f32_16x16x32_bf16 v[86:89], v[158:161], v[206:209], v[86:89]
	v_mfma_f32_16x16x32_bf16 v[94:97], v[170:173], v[202:205], v[94:97]
	v_mfma_f32_16x16x32_bf16 v[94:97], v[174:177], v[206:209], v[94:97]
	v_mfma_f32_16x16x32_bf16 v[66:69], v[146:149], v[210:213], v[66:69]
	v_mfma_f32_16x16x32_bf16 v[66:69], v[150:153], v[214:217], v[66:69]
	v_mfma_f32_16x16x32_bf16 v[74:77], v[162:165], v[210:213], v[74:77]
	v_mfma_f32_16x16x32_bf16 v[74:77], v[166:169], v[214:217], v[74:77]
	v_mfma_f32_16x16x32_bf16 v[70:73], v[154:157], v[210:213], v[70:73]
	v_mfma_f32_16x16x32_bf16 v[70:73], v[158:161], v[214:217], v[70:73]
	v_mfma_f32_16x16x32_bf16 v[78:81], v[170:173], v[210:213], v[78:81]
	v_mfma_f32_16x16x32_bf16 v[78:81], v[174:177], v[214:217], v[78:81]
	s_setprio 0
	s_barrier
; #define PG8_STAGE(bufoff, gbase, voff) do { _Pragma("unroll") for (int _i = 0; _i < 2; ++_i) \
;         __builtin_amdgcn_global_load_lds((const unsigned*)((const char*)(gbase) + (voff)[_i]), (PG8_LAS unsigned*)(lds + (bufoff) + ldsw + _i * 8192), 16, 0, 0); } while (0)
; #define PG8_LDA(dst, b, h) do { _Pragma("unroll") for (int m = 0; m < 4; ++m) _Pragma("unroll") for (int k = 0; k < 2; ++k) dst[m][k] = *(const PG8_LAS bf16x8*)(lds + PG8_SA(b, h) + aoff + m * 2048 + k * 1024); } while (0)
; #define PG8_MMA(ai, bj, At, Bt) do { __builtin_amdgcn_s_setprio(1); _Pragma("unroll") for (int m = 0; m < 4; ++m) _Pragma("unroll") for (int n = 0; n < 2; ++n) _Pragma("unroll") for (int k = 0; k < 2; ++k) \
;         acc[ai][bj][m][n] = __builtin_amdgcn_mfma_f32_16x16x32_bf16(Bt[n][k], At[m][k], acc[ai][bj][m][n], 0, 0, 0); __builtin_amdgcn_s_setprio(0); } while (0)
; #define PG8_WAIT_V(n) asm volatile("s_waitcnt vmcnt(" #n ")" ::: "memory")
; #define PG8_WAIT_L(n) asm volatile("s_waitcnt lgkmcnt(" #n ")" ::: "memory")
; #define PG8_BAR __builtin_amdgcn_s_barrier()
; #define PG8_SCHED __builtin_amdgcn_sched_barrier(0)
; template <class Epi, class Sched, bool ALIGN_EPI = false, bool SP2 = false>
; __device__ __forceinline__ void gemm_phase(PG8_LAS unsigned char* lds, const Gemm g, const Sched& S, const Epi& E) {
;     ...
;             PG8_LDA(At, 1, 1); PG8_STAGE(PG8_SB(1, 0), b3, voffB); PG8_STAGE(PG8_SB(1, 1), b3 + hstep, voffB); PG8_STAGE(PG8_SA(1, 0), a3, voffA);
;             PG8_WAIT_V(8); PG8_WAIT_L(0); PG8_BAR; PG8_MMA(1, 0, At, B0); PG8_MMA(1, 1, At, B1); PG8_BAR; PG8_SCHED;
;     ...
;         if constexpr (ALIGN_EPI) { if (wr == 0) PG8_BAR; }
	s_add_i32 s18, s18, s27
	v_lshl_add_u64 v[194:195], v[194:195], 0, s[30:31]
	s_mov_b32 m0, s18
	ds_read_b128 v[178:181], v144 offset:49152
	ds_read_b128 v[182:185], v144 offset:50176
	ds_read_b128 v[186:189], v144 offset:51200
	ds_read_b128 v[190:193], v144 offset:52224
	ds_read_b128 v[202:205], v144 offset:53248
	ds_read_b128 v[206:209], v144 offset:54272
	ds_read_b128 v[210:213], v144 offset:55296
	ds_read_b128 v[214:217], v144 offset:56320
	global_load_lds_dwordx4 v[194:195], off
	s_add_i32 m0, s18, 0x2000
	s_add_u32 s38, s56, 0x40080
	v_lshl_add_u64 v[194:195], v[218:219], 0, s[30:31]
	s_addc_u32 s39, s57, 0
	s_add_i32 s18, s83, s27
	global_load_lds_dwordx4 v[194:195], off
	v_lshl_add_u64 v[194:195], s[38:39], 0, v[0:1]
	s_mov_b32 m0, s18
	s_nop 0
	global_load_lds_dwordx4 v[194:195], off
	v_lshl_add_u64 v[194:195], s[38:39], 0, v[130:131]
	s_add_i32 m0, s18, 0x2000
	s_nop 0
	global_load_lds_dwordx4 v[194:195], off
	v_lshl_add_u64 v[194:195], v[220:221], 0, s[30:31]
	s_mov_b32 m0, s71
	s_nop 0
	global_load_lds_dwordx4 v[194:195], off
	v_lshl_add_u64 v[194:195], v[222:223], 0, s[30:31]
	s_mov_b32 m0, s72
	s_nop 0
	global_load_lds_dwordx4 v[194:195], off
	s_waitcnt vmcnt(8)
	s_waitcnt lgkmcnt(0)
	s_barrier
	s_setprio 1
	s_waitcnt lgkmcnt(0)
	v_mfma_f32_16x16x32_bf16 v[50:53], v[146:149], v[178:181], v[50:53]
	v_mfma_f32_16x16x32_bf16 v[50:53], v[150:153], v[182:185], v[50:53]
	v_mfma_f32_16x16x32_bf16 v[58:61], v[162:165], v[178:181], v[58:61]
	v_mfma_f32_16x16x32_bf16 v[58:61], v[166:169], v[182:185], v[58:61]
	v_mfma_f32_16x16x32_bf16 v[54:57], v[154:157], v[178:181], v[54:57]
	v_mfma_f32_16x16x32_bf16 v[54:57], v[158:161], v[182:185], v[54:57]
	v_mfma_f32_16x16x32_bf16 v[62:65], v[170:173], v[178:181], v[62:65]
	v_mfma_f32_16x16x32_bf16 v[62:65], v[174:177], v[182:185], v[62:65]
	v_mfma_f32_16x16x32_bf16 v[34:37], v[146:149], v[186:189], v[34:37]
	v_mfma_f32_16x16x32_bf16 v[34:37], v[150:153], v[190:193], v[34:37]
	v_mfma_f32_16x16x32_bf16 v[42:45], v[162:165], v[186:189], v[42:45]
	v_mfma_f32_16x16x32_bf16 v[42:45], v[166:169], v[190:193], v[42:45]
	v_mfma_f32_16x16x32_bf16 v[38:41], v[154:157], v[186:189], v[38:41]
	v_mfma_f32_16x16x32_bf16 v[38:41], v[158:161], v[190:193], v[38:41]
	v_mfma_f32_16x16x32_bf16 v[46:49], v[170:173], v[186:189], v[46:49]
	v_mfma_f32_16x16x32_bf16 v[46:49], v[174:177], v[190:193], v[46:49]
	v_mfma_f32_16x16x32_bf16 v[18:21], v[146:149], v[202:205], v[18:21]
	v_mfma_f32_16x16x32_bf16 v[18:21], v[150:153], v[206:209], v[18:21]
	v_mfma_f32_16x16x32_bf16 v[26:29], v[162:165], v[202:205], v[26:29]
	v_mfma_f32_16x16x32_bf16 v[26:29], v[166:169], v[206:209], v[26:29]
	v_mfma_f32_16x16x32_bf16 v[22:25], v[154:157], v[202:205], v[22:25]
	v_mfma_f32_16x16x32_bf16 v[22:25], v[158:161], v[206:209], v[22:25]
	v_mfma_f32_16x16x32_bf16 v[30:33], v[170:173], v[202:205], v[30:33]
	v_mfma_f32_16x16x32_bf16 v[30:33], v[174:177], v[206:209], v[30:33]
	v_mfma_f32_16x16x32_bf16 v[2:5], v[146:149], v[210:213], v[2:5]
	v_mfma_f32_16x16x32_bf16 v[2:5], v[150:153], v[214:217], v[2:5]
	v_mfma_f32_16x16x32_bf16 v[10:13], v[162:165], v[210:213], v[10:13]
	v_mfma_f32_16x16x32_bf16 v[10:13], v[166:169], v[214:217], v[10:13]
	v_mfma_f32_16x16x32_bf16 v[6:9], v[154:157], v[210:213], v[6:9]
	v_mfma_f32_16x16x32_bf16 v[6:9], v[158:161], v[214:217], v[6:9]
	v_mfma_f32_16x16x32_bf16 v[14:17], v[170:173], v[210:213], v[14:17]
	v_mfma_f32_16x16x32_bf16 v[14:17], v[174:177], v[214:217], v[14:17]
	s_setprio 0
	s_barrier
	s_add_i32 s82, s82, 2
	s_add_u32 s60, s60, 0x100
	s_addc_u32 s61, s61, 0
	s_add_u32 s80, s80, 0x100
	s_addc_u32 s81, s81, 0
	s_cmp_gt_u32 s82, 13
	s_cbranch_scc0 .LBB0_220
	s_and_b64 vcc, exec, s[44:45]
	s_cbranch_vccz .LBB0_223
	s_barrier

; #define PG8_STAGE(bufoff, gbase, voff) do { _Pragma("unroll") for (int _i = 0; _i < 2; ++_i) \
;         __builtin_amdgcn_global_load_lds((const unsigned*)((const char*)(gbase) + (voff)[_i]), (PG8_LAS unsigned*)(lds + (bufoff) + ldsw + _i * 8192), 16, 0, 0); } while (0)
; #define PG8_LDA(dst, b, h) do { _Pragma("unroll") for (int m = 0; m < 4; ++m) _Pragma("unroll") for (int k = 0; k < 2; ++k) dst[m][k] = *(const PG8_LAS bf16x8*)(lds + PG8_SA(b, h) + aoff + m * 2048 + k * 1024); } while (0)
; #define PG8_LDB(dst, b, h) do { _Pragma("unroll") for (int n = 0; n < 2; ++n) _Pragma("unroll") for (int k = 0; k < 2; ++k) dst[n][k] = *(const PG8_LAS bf16x8*)(lds + PG8_SB(b, h) + boff + n * 2048 + k * 1024); } while (0)
; #define PG8_MMA(ai, bj, At, Bt) do { __builtin_amdgcn_s_setprio(1); _Pragma("unroll") for (int m = 0; m < 4; ++m) _Pragma("unroll") for (int n = 0; n < 2; ++n) _Pragma("unroll") for (int k = 0; k < 2; ++k) \
;         acc[ai][bj][m][n] = __builtin_amdgcn_mfma_f32_16x16x32_bf16(Bt[n][k], At[m][k], acc[ai][bj][m][n], 0, 0, 0); __builtin_amdgcn_s_setprio(0); } while (0)
; #define PG8_WAIT_V(n) asm volatile("s_waitcnt vmcnt(" #n ")" ::: "memory")
; #define PG8_BAR __builtin_amdgcn_s_barrier()
; template <class Epi, class Sched, bool ALIGN_EPI = false, bool SP2 = false>
; __device__ __forceinline__ void gemm_phase(PG8_LAS unsigned char* lds, const Gemm g, const Sched& S, const Epi& E) {
;     ...
;         for (int t = 0; t < nt; t += 2) {
;             const bool last = (t == nt - 2);
;             const char* a1 = cA + (size_t)(t + 1) * kstep;
;             const char* a2 = last ? nA : cA + (size_t)(t + 2) * kstep; const char* b2 = last ? nB : cB + (size_t)(t + 2) * kstep;
;             const char* a3 = a2 + kstep; const char* b3 = b2 + kstep;
;             if (last && has_next) S.a_ready(nxt);
;             if constexpr (SP2) {
;             PG8_LDB(B0, 0, 0); PG8_LDB(B1, 0, 1); PG8_SCHED; PG8_LDA(At, 0, 0); PG8_STAGE(PG8_SA(1, 1), a1 + hstep, voffA);
;             PG8_WAIT_V(8); PG8_WAIT_L(0); PG8_BAR; PG8_MMA(0, 0, At, B0); PG8_MMA(0, 1, At, B1); PG8_BAR; PG8_SCHED;
;             PG8_LDA(At, 0, 1); PG8_STAGE(PG8_SB(0, 0), b2, voffB); PG8_STAGE(PG8_SB(0, 1), b2 + hstep, voffB); PG8_STAGE(PG8_SA(0, 0), a2, voffA);
;             PG8_WAIT_V(8); PG8_WAIT_L(0); PG8_BAR; PG8_MMA(1, 0, At, B0); PG8_MMA(1, 1, At, B1); PG8_BAR; PG8_SCHED;
.LBB0_274:
	s_add_i32 vcc_lo, s46, 2
	s_add_u32 s38, s48, 0x80
	s_addc_u32 s39, s49, 0
	s_add_i32 vcc_hi, 0, 0x10000
	s_cmp_eq_u32 s99, s46
	s_cselect_b32 s47, s81, s39
	s_cselect_b32 s46, s80, s38
	s_cselect_b32 s39, s83, s51
	s_cselect_b32 s38, s82, s50
	s_add_i32 s18, 0, 0x14000
	v_add_u32_e32 v142, vcc_hi, v245
	v_add_u32_e32 v158, s18, v245
	ds_read_b128 v[110:113], v142
	ds_read_b128 v[118:121], v142 offset:1024
	ds_read_b128 v[138:141], v142 offset:2048
	ds_read_b128 v[142:145], v142 offset:3072
	ds_read_b128 v[146:149], v158
	ds_read_b128 v[150:153], v158 offset:1024
	ds_read_b128 v[154:157], v158 offset:2048
	ds_read_b128 v[158:161], v158 offset:3072
	v_lshl_add_u64 v[210:211], s[48:49], 0, v[206:207]
	s_add_i32 m0, s92, 0xc000
	ds_read_b128 v[162:165], v247
	ds_read_b128 v[166:169], v247 offset:1024
	ds_read_b128 v[170:173], v247 offset:2048
	ds_read_b128 v[174:177], v247 offset:3072
	ds_read_b128 v[178:181], v247 offset:4096
	ds_read_b128 v[182:185], v247 offset:5120
	ds_read_b128 v[186:189], v247 offset:6144
	ds_read_b128 v[190:193], v247 offset:7168
	global_load_lds_dwordx4 v[210:211], off
	v_lshl_add_u64 v[210:211], s[48:49], 0, v[208:209]
	s_add_i32 m0, s92, 0xe000
	s_nop 0
	global_load_lds_dwordx4 v[210:211], off
	s_waitcnt vmcnt(8)
	s_waitcnt lgkmcnt(0)
	s_barrier
	s_setprio 1
	s_waitcnt lgkmcnt(0)
	v_mfma_f32_16x16x32_bf16 v[130:133], v[110:113], v[162:165], v[130:133]
	v_mfma_f32_16x16x32_bf16 v[130:133], v[118:121], v[166:169], v[130:133]
	v_mfma_f32_16x16x32_bf16 v[126:129], v[146:149], v[162:165], v[126:129]
	v_mfma_f32_16x16x32_bf16 v[126:129], v[150:153], v[166:169], v[126:129]
	v_mfma_f32_16x16x32_bf16 v[134:137], v[138:141], v[162:165], v[134:137]
	v_mfma_f32_16x16x32_bf16 v[134:137], v[142:145], v[166:169], v[134:137]
	v_mfma_f32_16x16x32_bf16 v[122:125], v[154:157], v[162:165], v[122:125]
	v_mfma_f32_16x16x32_bf16 v[122:125], v[158:161], v[166:169], v[122:125]
	v_mfma_f32_16x16x32_bf16 v[114:117], v[110:113], v[170:173], v[114:117]
	v_mfma_f32_16x16x32_bf16 v[114:117], v[118:121], v[174:177], v[114:117]
	v_mfma_f32_16x16x32_bf16 v[102:105], v[146:149], v[170:173], v[102:105]
	v_mfma_f32_16x16x32_bf16 v[102:105], v[150:153], v[174:177], v[102:105]
	v_mfma_f32_16x16x32_bf16 v[106:109], v[138:141], v[170:173], v[106:109]
	v_mfma_f32_16x16x32_bf16 v[106:109], v[142:145], v[174:177], v[106:109]
	v_mfma_f32_16x16x32_bf16 v[98:101], v[154:157], v[170:173], v[98:101]
	v_mfma_f32_16x16x32_bf16 v[98:101], v[158:161], v[174:177], v[98:101]
	v_mfma_f32_16x16x32_bf16 v[94:97], v[110:113], v[178:181], v[94:97]
	v_mfma_f32_16x16x32_bf16 v[94:97], v[118:121], v[182:185], v[94:97]
	v_mfma_f32_16x16x32_bf16 v[86:89], v[146:149], v[178:181], v[86:89]
	v_mfma_f32_16x16x32_bf16 v[86:89], v[150:153], v[182:185], v[86:89]
	v_mfma_f32_16x16x32_bf16 v[90:93], v[138:141], v[178:181], v[90:93]
	v_mfma_f32_16x16x32_bf16 v[90:93], v[142:145], v[182:185], v[90:93]
	v_mfma_f32_16x16x32_bf16 v[82:85], v[154:157], v[178:181], v[82:85]
	v_mfma_f32_16x16x32_bf16 v[82:85], v[158:161], v[182:185], v[82:85]
	v_mfma_f32_16x16x32_bf16 v[78:81], v[110:113], v[186:189], v[78:81]
	v_mfma_f32_16x16x32_bf16 v[78:81], v[118:121], v[190:193], v[78:81]
	v_mfma_f32_16x16x32_bf16 v[70:73], v[146:149], v[186:189], v[70:73]
	v_mfma_f32_16x16x32_bf16 v[70:73], v[150:153], v[190:193], v[70:73]
	v_mfma_f32_16x16x32_bf16 v[74:77], v[138:141], v[186:189], v[74:77]
	v_mfma_f32_16x16x32_bf16 v[74:77], v[142:145], v[190:193], v[74:77]
	v_mfma_f32_16x16x32_bf16 v[66:69], v[154:157], v[186:189], v[66:69]
	v_mfma_f32_16x16x32_bf16 v[66:69], v[158:161], v[190:193], v[66:69]
	s_setprio 0
	s_barrier
	s_add_i32 vcc_hi, vcc_hi, s6
	v_lshl_add_u64 v[210:211], s[38:39], 0, v[0:1]
	s_mov_b32 m0, vcc_hi
	ds_read_b128 v[162:165], v247 offset:16384
	ds_read_b128 v[166:169], v247 offset:17408
	ds_read_b128 v[170:173], v247 offset:18432
	ds_read_b128 v[174:177], v247 offset:19456
	ds_read_b128 v[178:181], v247 offset:20480
	ds_read_b128 v[182:185], v247 offset:21504
	ds_read_b128 v[186:189], v247 offset:22528
	ds_read_b128 v[190:193], v247 offset:23552
	global_load_lds_dwordx4 v[210:211], off
	s_add_i32 m0, vcc_hi, 0x2000
	v_lshl_add_u64 v[212:213], s[38:39], 0, v[204:205]
	s_add_u32 s38, s38, s58
	s_addc_u32 s39, s39, 0
	s_add_i32 s18, s18, s6
	global_load_lds_dwordx4 v[212:213], off
	v_lshl_add_u64 v[214:215], s[38:39], 0, v[0:1]
	s_mov_b32 m0, s18
	v_lshl_add_u64 v[216:217], s[38:39], 0, v[204:205]
	global_load_lds_dwordx4 v[214:215], off
	s_add_i32 m0, s18, 0x2000
	v_lshl_add_u64 v[218:219], s[46:47], 0, v[194:195]
	global_load_lds_dwordx4 v[216:217], off
	s_mov_b32 m0, s92
	v_lshl_add_u64 v[220:221], s[46:47], 0, v[202:203]
	global_load_lds_dwordx4 v[218:219], off
	s_mov_b32 m0, s93
	s_nop 0
	global_load_lds_dwordx4 v[220:221], off
	s_waitcnt vmcnt(8)
	s_waitcnt lgkmcnt(0)
	s_barrier
; #define PG8_STAGE(bufoff, gbase, voff) do { _Pragma("unroll") for (int _i = 0; _i < 2; ++_i) \
;         __builtin_amdgcn_global_load_lds((const unsigned*)((const char*)(gbase) + (voff)[_i]), (PG8_LAS unsigned*)(lds + (bufoff) + ldsw + _i * 8192), 16, 0, 0); } while (0)
; #define PG8_LDA(dst, b, h) do { _Pragma("unroll") for (int m = 0; m < 4; ++m) _Pragma("unroll") for (int k = 0; k < 2; ++k) dst[m][k] = *(const PG8_LAS bf16x8*)(lds + PG8_SA(b, h) + aoff + m * 2048 + k * 1024); } while (0)
; #define PG8_LDB(dst, b, h) do { _Pragma("unroll") for (int n = 0; n < 2; ++n) _Pragma("unroll") for (int k = 0; k < 2; ++k) dst[n][k] = *(const PG8_LAS bf16x8*)(lds + PG8_SB(b, h) + boff + n * 2048 + k * 1024); } while (0)
; #define PG8_MMA(ai, bj, At, Bt) do { __builtin_amdgcn_s_setprio(1); _Pragma("unroll") for (int m = 0; m < 4; ++m) _Pragma("unroll") for (int n = 0; n < 2; ++n) _Pragma("unroll") for (int k = 0; k < 2; ++k) \
;         acc[ai][bj][m][n] = __builtin_amdgcn_mfma_f32_16x16x32_bf16(Bt[n][k], At[m][k], acc[ai][bj][m][n], 0, 0, 0); __builtin_amdgcn_s_setprio(0); } while (0)
; #define PG8_WAIT_V(n) asm volatile("s_waitcnt vmcnt(" #n ")" ::: "memory")
; #define PG8_WAIT_L(n) asm volatile("s_waitcnt lgkmcnt(" #n ")" ::: "memory")
; #define PG8_BAR __builtin_amdgcn_s_barrier()
; #define PG8_SCHED __builtin_amdgcn_sched_barrier(0)
; template <class Epi, class Sched, bool ALIGN_EPI = false, bool SP2 = false>
; __device__ __forceinline__ void gemm_phase(PG8_LAS unsigned char* lds, const Gemm g, const Sched& S, const Epi& E) {
;     ...
;             PG8_WAIT_V(8); PG8_WAIT_L(0); PG8_BAR; PG8_MMA(1, 0, At, B0); PG8_MMA(1, 1, At, B1); PG8_BAR; PG8_SCHED;
;             PG8_LDB(B0, 1, 0); PG8_LDB(B1, 1, 1); PG8_SCHED; PG8_LDA(At, 1, 0); PG8_STAGE(PG8_SA(0, 1), a2 + hstep, voffA);
;             PG8_WAIT_V(8); PG8_WAIT_L(0); PG8_BAR; PG8_MMA(0, 0, At, B0); PG8_MMA(0, 1, At, B1); PG8_BAR; PG8_SCHED;
	s_setprio 1
	s_waitcnt lgkmcnt(0)
	v_mfma_f32_16x16x32_bf16 v[62:65], v[110:113], v[162:165], v[62:65]
	v_mfma_f32_16x16x32_bf16 v[62:65], v[118:121], v[166:169], v[62:65]
	v_mfma_f32_16x16x32_bf16 v[54:57], v[146:149], v[162:165], v[54:57]
	v_mfma_f32_16x16x32_bf16 v[54:57], v[150:153], v[166:169], v[54:57]
	v_mfma_f32_16x16x32_bf16 v[58:61], v[138:141], v[162:165], v[58:61]
	v_mfma_f32_16x16x32_bf16 v[58:61], v[142:145], v[166:169], v[58:61]
	v_mfma_f32_16x16x32_bf16 v[50:53], v[154:157], v[162:165], v[50:53]
	v_mfma_f32_16x16x32_bf16 v[50:53], v[158:161], v[166:169], v[50:53]
	v_mfma_f32_16x16x32_bf16 v[46:49], v[110:113], v[170:173], v[46:49]
	v_mfma_f32_16x16x32_bf16 v[46:49], v[118:121], v[174:177], v[46:49]
	v_mfma_f32_16x16x32_bf16 v[38:41], v[146:149], v[170:173], v[38:41]
	v_mfma_f32_16x16x32_bf16 v[38:41], v[150:153], v[174:177], v[38:41]
	v_mfma_f32_16x16x32_bf16 v[42:45], v[138:141], v[170:173], v[42:45]
	v_mfma_f32_16x16x32_bf16 v[42:45], v[142:145], v[174:177], v[42:45]
	v_mfma_f32_16x16x32_bf16 v[34:37], v[154:157], v[170:173], v[34:37]
	v_mfma_f32_16x16x32_bf16 v[34:37], v[158:161], v[174:177], v[34:37]
	v_mfma_f32_16x16x32_bf16 v[30:33], v[110:113], v[178:181], v[30:33]
	v_mfma_f32_16x16x32_bf16 v[30:33], v[118:121], v[182:185], v[30:33]
	v_mfma_f32_16x16x32_bf16 v[22:25], v[146:149], v[178:181], v[22:25]
	v_mfma_f32_16x16x32_bf16 v[22:25], v[150:153], v[182:185], v[22:25]
	v_mfma_f32_16x16x32_bf16 v[26:29], v[138:141], v[178:181], v[26:29]
	v_mfma_f32_16x16x32_bf16 v[26:29], v[142:145], v[182:185], v[26:29]
	v_mfma_f32_16x16x32_bf16 v[18:21], v[154:157], v[178:181], v[18:21]
	v_mfma_f32_16x16x32_bf16 v[18:21], v[158:161], v[182:185], v[18:21]
	v_mfma_f32_16x16x32_bf16 v[14:17], v[110:113], v[186:189], v[14:17]
	v_mfma_f32_16x16x32_bf16 v[14:17], v[118:121], v[190:193], v[14:17]
	v_mfma_f32_16x16x32_bf16 v[6:9], v[146:149], v[186:189], v[6:9]
	v_mfma_f32_16x16x32_bf16 v[6:9], v[150:153], v[190:193], v[6:9]
	v_mfma_f32_16x16x32_bf16 v[10:13], v[138:141], v[186:189], v[10:13]
	v_mfma_f32_16x16x32_bf16 v[10:13], v[142:145], v[190:193], v[10:13]
	v_mfma_f32_16x16x32_bf16 v[2:5], v[154:157], v[186:189], v[2:5]
	v_mfma_f32_16x16x32_bf16 v[2:5], v[158:161], v[190:193], v[2:5]
	s_setprio 0
	s_barrier
	s_add_i32 s18, 0, 0x18000
	s_add_i32 vcc_hi, 0, 0x1c000
	v_add_u32_e32 v142, s18, v245
	v_add_u32_e32 v158, vcc_hi, v245
	ds_read_b128 v[110:113], v142
	ds_read_b128 v[118:121], v142 offset:1024
	ds_read_b128 v[138:141], v142 offset:2048
	ds_read_b128 v[142:145], v142 offset:3072
	ds_read_b128 v[146:149], v158
	ds_read_b128 v[150:153], v158 offset:1024
	ds_read_b128 v[154:157], v158 offset:2048
	ds_read_b128 v[158:161], v158 offset:3072
	s_add_u32 s38, s46, s58
	s_addc_u32 s39, s47, 0
	s_mov_b32 m0, s94
	v_lshl_add_u64 v[222:223], s[38:39], 0, v[194:195]
	ds_read_b128 v[162:165], v247 offset:32768
	ds_read_b128 v[166:169], v247 offset:33792
	ds_read_b128 v[170:173], v247 offset:34816
	ds_read_b128 v[174:177], v247 offset:35840
	ds_read_b128 v[178:181], v247 offset:36864
	ds_read_b128 v[182:185], v247 offset:37888
	ds_read_b128 v[186:189], v247 offset:38912
	ds_read_b128 v[190:193], v247 offset:39936
	global_load_lds_dwordx4 v[222:223], off
	v_lshl_add_u64 v[222:223], s[38:39], 0, v[202:203]
	s_mov_b32 m0, s95
	s_nop 0
	global_load_lds_dwordx4 v[222:223], off
	s_waitcnt vmcnt(8)
	s_waitcnt lgkmcnt(0)
	s_barrier
	s_setprio 1
	s_waitcnt lgkmcnt(0)
	v_mfma_f32_16x16x32_bf16 v[130:133], v[110:113], v[162:165], v[130:133]
	v_mfma_f32_16x16x32_bf16 v[130:133], v[118:121], v[166:169], v[130:133]
	v_mfma_f32_16x16x32_bf16 v[126:129], v[146:149], v[162:165], v[126:129]
	v_mfma_f32_16x16x32_bf16 v[126:129], v[150:153], v[166:169], v[126:129]
	v_mfma_f32_16x16x32_bf16 v[134:137], v[138:141], v[162:165], v[134:137]
	v_mfma_f32_16x16x32_bf16 v[134:137], v[142:145], v[166:169], v[134:137]
	v_mfma_f32_16x16x32_bf16 v[122:125], v[154:157], v[162:165], v[122:125]
	v_mfma_f32_16x16x32_bf16 v[122:125], v[158:161], v[166:169], v[122:125]
	v_mfma_f32_16x16x32_bf16 v[114:117], v[110:113], v[170:173], v[114:117]
	v_mfma_f32_16x16x32_bf16 v[114:117], v[118:121], v[174:177], v[114:117]
	v_mfma_f32_16x16x32_bf16 v[102:105], v[146:149], v[170:173], v[102:105]
	v_mfma_f32_16x16x32_bf16 v[102:105], v[150:153], v[174:177], v[102:105]
	v_mfma_f32_16x16x32_bf16 v[106:109], v[138:141], v[170:173], v[106:109]
	v_mfma_f32_16x16x32_bf16 v[106:109], v[142:145], v[174:177], v[106:109]
	v_mfma_f32_16x16x32_bf16 v[98:101], v[154:157], v[170:173], v[98:101]
	v_mfma_f32_16x16x32_bf16 v[98:101], v[158:161], v[174:177], v[98:101]
	v_mfma_f32_16x16x32_bf16 v[94:97], v[110:113], v[178:181], v[94:97]
	v_mfma_f32_16x16x32_bf16 v[94:97], v[118:121], v[182:185], v[94:97]
	v_mfma_f32_16x16x32_bf16 v[86:89], v[146:149], v[178:181], v[86:89]
	v_mfma_f32_16x16x32_bf16 v[86:89], v[150:153], v[182:185], v[86:89]
	v_mfma_f32_16x16x32_bf16 v[90:93], v[138:141], v[178:181], v[90:93]
	v_mfma_f32_16x16x32_bf16 v[90:93], v[142:145], v[182:185], v[90:93]
	v_mfma_f32_16x16x32_bf16 v[82:85], v[154:157], v[178:181], v[82:85]
	v_mfma_f32_16x16x32_bf16 v[82:85], v[158:161], v[182:185], v[82:85]
	v_mfma_f32_16x16x32_bf16 v[78:81], v[110:113], v[186:189], v[78:81]
	v_mfma_f32_16x16x32_bf16 v[78:81], v[118:121], v[190:193], v[78:81]
	v_mfma_f32_16x16x32_bf16 v[70:73], v[146:149], v[186:189], v[70:73]
	v_mfma_f32_16x16x32_bf16 v[70:73], v[150:153], v[190:193], v[70:73]
	v_mfma_f32_16x16x32_bf16 v[74:77], v[138:141], v[186:189], v[74:77]
	v_mfma_f32_16x16x32_bf16 v[74:77], v[142:145], v[190:193], v[74:77]
	v_mfma_f32_16x16x32_bf16 v[66:69], v[154:157], v[186:189], v[66:69]
	v_mfma_f32_16x16x32_bf16 v[66:69], v[158:161], v[190:193], v[66:69]
	s_setprio 0
	s_barrier
; #define PG8_STAGE(bufoff, gbase, voff) do { _Pragma("unroll") for (int _i = 0; _i < 2; ++_i) \
;         __builtin_amdgcn_global_load_lds((const unsigned*)((const char*)(gbase) + (voff)[_i]), (PG8_LAS unsigned*)(lds + (bufoff) + ldsw + _i * 8192), 16, 0, 0); } while (0)
; #define PG8_LDA(dst, b, h) do { _Pragma("unroll") for (int m = 0; m < 4; ++m) _Pragma("unroll") for (int k = 0; k < 2; ++k) dst[m][k] = *(const PG8_LAS bf16x8*)(lds + PG8_SA(b, h) + aoff + m * 2048 + k * 1024); } while (0)
; #define PG8_MMA(ai, bj, At, Bt) do { __builtin_amdgcn_s_setprio(1); _Pragma("unroll") for (int m = 0; m < 4; ++m) _Pragma("unroll") for (int n = 0; n < 2; ++n) _Pragma("unroll") for (int k = 0; k < 2; ++k) \
;         acc[ai][bj][m][n] = __builtin_amdgcn_mfma_f32_16x16x32_bf16(Bt[n][k], At[m][k], acc[ai][bj][m][n], 0, 0, 0); __builtin_amdgcn_s_setprio(0); } while (0)
; #define PG8_WAIT_V(n) asm volatile("s_waitcnt vmcnt(" #n ")" ::: "memory")
; #define PG8_WAIT_L(n) asm volatile("s_waitcnt lgkmcnt(" #n ")" ::: "memory")
; #define PG8_BAR __builtin_amdgcn_s_barrier()
; #define PG8_SCHED __builtin_amdgcn_sched_barrier(0)
; template <class Epi, class Sched, bool ALIGN_EPI = false, bool SP2 = false>
; __device__ __forceinline__ void gemm_phase(PG8_LAS unsigned char* lds, const Gemm g, const Sched& S, const Epi& E) {
;     ...
;             PG8_LDA(At, 1, 1); PG8_STAGE(PG8_SB(1, 0), b3, voffB); PG8_STAGE(PG8_SB(1, 1), b3 + hstep, voffB); PG8_STAGE(PG8_SA(1, 0), a3, voffA);
;             PG8_WAIT_V(8); PG8_WAIT_L(0); PG8_BAR; PG8_MMA(1, 0, At, B0); PG8_MMA(1, 1, At, B1); PG8_BAR; PG8_SCHED;
;     ...
;         if constexpr (ALIGN_EPI) { if (wr == 0) PG8_BAR; }
	s_add_i32 s18, s18, s6
	v_lshl_add_u64 v[210:211], v[210:211], 0, s[30:31]
	s_mov_b32 m0, s18
	ds_read_b128 v[162:165], v247 offset:49152
	ds_read_b128 v[166:169], v247 offset:50176
	ds_read_b128 v[170:173], v247 offset:51200
	ds_read_b128 v[174:177], v247 offset:52224
	ds_read_b128 v[178:181], v247 offset:53248
	ds_read_b128 v[182:185], v247 offset:54272
	ds_read_b128 v[186:189], v247 offset:55296
	ds_read_b128 v[190:193], v247 offset:56320
	global_load_lds_dwordx4 v[210:211], off
	v_lshl_add_u64 v[210:211], v[212:213], 0, s[30:31]
	s_add_i32 m0, s18, 0x2000
	s_add_i32 s18, vcc_hi, s6
	global_load_lds_dwordx4 v[210:211], off
	v_lshl_add_u64 v[210:211], v[214:215], 0, s[30:31]
	s_mov_b32 m0, s18
	s_nop 0
	global_load_lds_dwordx4 v[210:211], off
	v_lshl_add_u64 v[210:211], v[216:217], 0, s[30:31]
	s_add_i32 m0, s18, 0x2000
	s_nop 0
	global_load_lds_dwordx4 v[210:211], off
	v_lshl_add_u64 v[210:211], v[218:219], 0, s[30:31]
	s_mov_b32 m0, s97
	s_nop 0
	global_load_lds_dwordx4 v[210:211], off
	v_lshl_add_u64 v[210:211], v[220:221], 0, s[30:31]
	s_mov_b32 m0, s98
	s_nop 0
	global_load_lds_dwordx4 v[210:211], off
	s_waitcnt vmcnt(8)
	s_waitcnt lgkmcnt(0)
	s_barrier
	s_setprio 1
	s_waitcnt lgkmcnt(0)
	v_mfma_f32_16x16x32_bf16 v[62:65], v[110:113], v[162:165], v[62:65]
	v_mfma_f32_16x16x32_bf16 v[62:65], v[118:121], v[166:169], v[62:65]
	v_mfma_f32_16x16x32_bf16 v[54:57], v[146:149], v[162:165], v[54:57]
	v_mfma_f32_16x16x32_bf16 v[54:57], v[150:153], v[166:169], v[54:57]
	v_mfma_f32_16x16x32_bf16 v[58:61], v[138:141], v[162:165], v[58:61]
	v_mfma_f32_16x16x32_bf16 v[58:61], v[142:145], v[166:169], v[58:61]
	v_mfma_f32_16x16x32_bf16 v[50:53], v[154:157], v[162:165], v[50:53]
	v_mfma_f32_16x16x32_bf16 v[50:53], v[158:161], v[166:169], v[50:53]
	v_mfma_f32_16x16x32_bf16 v[46:49], v[110:113], v[170:173], v[46:49]
	v_mfma_f32_16x16x32_bf16 v[46:49], v[118:121], v[174:177], v[46:49]
	v_mfma_f32_16x16x32_bf16 v[38:41], v[146:149], v[170:173], v[38:41]
	v_mfma_f32_16x16x32_bf16 v[38:41], v[150:153], v[174:177], v[38:41]
	v_mfma_f32_16x16x32_bf16 v[42:45], v[138:141], v[170:173], v[42:45]
	v_mfma_f32_16x16x32_bf16 v[42:45], v[142:145], v[174:177], v[42:45]
	v_mfma_f32_16x16x32_bf16 v[34:37], v[154:157], v[170:173], v[34:37]
	v_mfma_f32_16x16x32_bf16 v[34:37], v[158:161], v[174:177], v[34:37]
	v_mfma_f32_16x16x32_bf16 v[30:33], v[110:113], v[178:181], v[30:33]
	v_mfma_f32_16x16x32_bf16 v[30:33], v[118:121], v[182:185], v[30:33]
	v_mfma_f32_16x16x32_bf16 v[22:25], v[146:149], v[178:181], v[22:25]
	v_mfma_f32_16x16x32_bf16 v[22:25], v[150:153], v[182:185], v[22:25]
	v_mfma_f32_16x16x32_bf16 v[26:29], v[138:141], v[178:181], v[26:29]
	v_mfma_f32_16x16x32_bf16 v[26:29], v[142:145], v[182:185], v[26:29]
	v_mfma_f32_16x16x32_bf16 v[18:21], v[154:157], v[178:181], v[18:21]
	v_mfma_f32_16x16x32_bf16 v[18:21], v[158:161], v[182:185], v[18:21]
	v_mfma_f32_16x16x32_bf16 v[14:17], v[110:113], v[186:189], v[14:17]
	v_mfma_f32_16x16x32_bf16 v[14:17], v[118:121], v[190:193], v[14:17]
	v_mfma_f32_16x16x32_bf16 v[6:9], v[146:149], v[186:189], v[6:9]
	v_mfma_f32_16x16x32_bf16 v[6:9], v[150:153], v[190:193], v[6:9]
	v_mfma_f32_16x16x32_bf16 v[10:13], v[138:141], v[186:189], v[10:13]
	v_mfma_f32_16x16x32_bf16 v[10:13], v[142:145], v[190:193], v[10:13]
	v_mfma_f32_16x16x32_bf16 v[2:5], v[154:157], v[186:189], v[2:5]
	v_mfma_f32_16x16x32_bf16 v[2:5], v[158:161], v[190:193], v[2:5]
	s_setprio 0
	s_barrier
	s_add_u32 s48, s48, 0x100
	s_addc_u32 s49, s49, 0
	s_add_u32 s50, s50, 0x100
	s_addc_u32 s51, s51, 0
	s_cmp_ge_u32 vcc_lo, s96
	s_mov_b32 s46, vcc_lo
	s_cbranch_scc0 .LBB0_274
	s_and_b64 vcc, exec, s[72:73]
	s_cbranch_vccz .LBB0_277
	s_barrier

; #define PG8_STAGE(bufoff, gbase, voff) do { _Pragma("unroll") for (int _i = 0; _i < 2; ++_i) \
;         __builtin_amdgcn_global_load_lds((const unsigned*)((const char*)(gbase) + (voff)[_i]), (PG8_LAS unsigned*)(lds + (bufoff) + ldsw + _i * 8192), 16, 0, 0); } while (0)
; #define PG8_LDA(dst, b, h) do { _Pragma("unroll") for (int m = 0; m < 4; ++m) _Pragma("unroll") for (int k = 0; k < 2; ++k) dst[m][k] = *(const PG8_LAS bf16x8*)(lds + PG8_SA(b, h) + aoff + m * 2048 + k * 1024); } while (0)
; #define PG8_LDB(dst, b, h) do { _Pragma("unroll") for (int n = 0; n < 2; ++n) _Pragma("unroll") for (int k = 0; k < 2; ++k) dst[n][k] = *(const PG8_LAS bf16x8*)(lds + PG8_SB(b, h) + boff + n * 2048 + k * 1024); } while (0)
; #define PG8_MMA(ai, bj, At, Bt) do { __builtin_amdgcn_s_setprio(1); _Pragma("unroll") for (int m = 0; m < 4; ++m) _Pragma("unroll") for (int n = 0; n < 2; ++n) _Pragma("unroll") for (int k = 0; k < 2; ++k) \
;         acc[ai][bj][m][n] = __builtin_amdgcn_mfma_f32_16x16x32_bf16(Bt[n][k], At[m][k], acc[ai][bj][m][n], 0, 0, 0); __builtin_amdgcn_s_setprio(0); } while (0)
; #define PG8_WAIT_V(n) asm volatile("s_waitcnt vmcnt(" #n ")" ::: "memory")
; #define PG8_BAR __builtin_amdgcn_s_barrier()
; template <class Epi, class Sched, bool ALIGN_EPI = false, bool SP2 = false>
; __device__ __forceinline__ void gemm_phase(PG8_LAS unsigned char* lds, const Gemm g, const Sched& S, const Epi& E) {
;     ...
;         for (int t = 0; t < nt; t += 2) {
;             const bool last = (t == nt - 2);
;             const char* a1 = cA + (size_t)(t + 1) * kstep;
;             const char* a2 = last ? nA : cA + (size_t)(t + 2) * kstep; const char* b2 = last ? nB : cB + (size_t)(t + 2) * kstep;
;             const char* a3 = a2 + kstep; const char* b3 = b2 + kstep;
;             if (last && has_next) S.a_ready(nxt);
;             if constexpr (SP2) {
;             PG8_LDB(B0, 0, 0); PG8_LDB(B1, 0, 1); PG8_SCHED; PG8_LDA(At, 0, 0); PG8_STAGE(PG8_SA(1, 1), a1 + hstep, voffA);
;             PG8_WAIT_V(8); PG8_WAIT_L(0); PG8_BAR; PG8_MMA(0, 0, At, B0); PG8_MMA(0, 1, At, B1); PG8_BAR; PG8_SCHED;
;             PG8_LDA(At, 0, 1); PG8_STAGE(PG8_SB(0, 0), b2, voffB); PG8_STAGE(PG8_SB(0, 1), b2 + hstep, voffB); PG8_STAGE(PG8_SA(0, 0), a2, voffA);
;             PG8_WAIT_V(8); PG8_WAIT_L(0); PG8_BAR; PG8_MMA(1, 0, At, B0); PG8_MMA(1, 1, At, B1); PG8_BAR; PG8_SCHED;
.LBB0_408:
	s_add_u32 s38, s48, 0xfffc0080
	s_addc_u32 s39, s49, -1
	s_add_i32 s85, 0, 0x10000
	s_cmp_eq_u32 s84, 12
	s_cselect_b32 s73, s21, s39
	s_cselect_b32 s72, s27, s38
	v_add_u32_e32 v0, s85, v167
	s_cselect_b32 s47, s29, s69
	s_cselect_b32 s46, s33, s53
	s_add_i32 s38, 0, 0x14000
	ds_read_b128 v[142:145], v0
	ds_read_b128 v[146:149], v0 offset:1024
	ds_read_b128 v[150:153], v0 offset:2048
	ds_read_b128 v[154:157], v0 offset:3072
	v_add_u32_e32 v0, s38, v167
	ds_read_b128 v[158:161], v0
	ds_read_b128 v[162:165], v0 offset:1024
	ds_read_b128 v[172:175], v0 offset:2048
	ds_read_b128 v[176:179], v0 offset:3072
	v_lshl_add_u64 v[218:219], s[48:49], 0, v[138:139]
	s_add_i32 m0, s76, 0xc000
	ds_read_b128 v[180:183], v170
	ds_read_b128 v[184:187], v170 offset:1024
	ds_read_b128 v[188:191], v170 offset:2048
	ds_read_b128 v[192:195], v170 offset:3072
	ds_read_b128 v[202:205], v170 offset:4096
	ds_read_b128 v[206:209], v170 offset:5120
	ds_read_b128 v[210:213], v170 offset:6144
	ds_read_b128 v[214:217], v170 offset:7168
	global_load_lds_dwordx4 v[218:219], off
	v_lshl_add_u64 v[218:219], s[48:49], 0, v[140:141]
	s_add_i32 m0, s76, 0xe000
	s_nop 0
	global_load_lds_dwordx4 v[218:219], off
	s_waitcnt vmcnt(8)
	s_waitcnt lgkmcnt(0)
	s_barrier
	s_setprio 1
	s_waitcnt lgkmcnt(0)
	v_mfma_f32_16x16x32_bf16 v[122:125], v[142:145], v[180:183], v[122:125]
	v_mfma_f32_16x16x32_bf16 v[122:125], v[146:149], v[184:187], v[122:125]
	v_mfma_f32_16x16x32_bf16 v[114:117], v[158:161], v[180:183], v[114:117]
	v_mfma_f32_16x16x32_bf16 v[114:117], v[162:165], v[184:187], v[114:117]
	v_mfma_f32_16x16x32_bf16 v[126:129], v[150:153], v[180:183], v[126:129]
	v_mfma_f32_16x16x32_bf16 v[126:129], v[154:157], v[184:187], v[126:129]
	v_mfma_f32_16x16x32_bf16 v[118:121], v[172:175], v[180:183], v[118:121]
	v_mfma_f32_16x16x32_bf16 v[118:121], v[176:179], v[184:187], v[118:121]
	v_mfma_f32_16x16x32_bf16 v[106:109], v[142:145], v[188:191], v[106:109]
	v_mfma_f32_16x16x32_bf16 v[106:109], v[146:149], v[192:195], v[106:109]
	v_mfma_f32_16x16x32_bf16 v[98:101], v[158:161], v[188:191], v[98:101]
	v_mfma_f32_16x16x32_bf16 v[98:101], v[162:165], v[192:195], v[98:101]
	v_mfma_f32_16x16x32_bf16 v[110:113], v[150:153], v[188:191], v[110:113]
	v_mfma_f32_16x16x32_bf16 v[110:113], v[154:157], v[192:195], v[110:113]
	v_mfma_f32_16x16x32_bf16 v[102:105], v[172:175], v[188:191], v[102:105]
	v_mfma_f32_16x16x32_bf16 v[102:105], v[176:179], v[192:195], v[102:105]
	v_mfma_f32_16x16x32_bf16 v[90:93], v[142:145], v[202:205], v[90:93]
	v_mfma_f32_16x16x32_bf16 v[90:93], v[146:149], v[206:209], v[90:93]
	v_mfma_f32_16x16x32_bf16 v[82:85], v[158:161], v[202:205], v[82:85]
	v_mfma_f32_16x16x32_bf16 v[82:85], v[162:165], v[206:209], v[82:85]
	v_mfma_f32_16x16x32_bf16 v[94:97], v[150:153], v[202:205], v[94:97]
	v_mfma_f32_16x16x32_bf16 v[94:97], v[154:157], v[206:209], v[94:97]
	v_mfma_f32_16x16x32_bf16 v[86:89], v[172:175], v[202:205], v[86:89]
	v_mfma_f32_16x16x32_bf16 v[86:89], v[176:179], v[206:209], v[86:89]
	v_mfma_f32_16x16x32_bf16 v[74:77], v[142:145], v[210:213], v[74:77]
	v_mfma_f32_16x16x32_bf16 v[74:77], v[146:149], v[214:217], v[74:77]
	v_mfma_f32_16x16x32_bf16 v[66:69], v[158:161], v[210:213], v[66:69]
	v_mfma_f32_16x16x32_bf16 v[66:69], v[162:165], v[214:217], v[66:69]
	v_mfma_f32_16x16x32_bf16 v[78:81], v[150:153], v[210:213], v[78:81]
	v_mfma_f32_16x16x32_bf16 v[78:81], v[154:157], v[214:217], v[78:81]
	v_mfma_f32_16x16x32_bf16 v[70:73], v[172:175], v[210:213], v[70:73]
	v_mfma_f32_16x16x32_bf16 v[70:73], v[176:179], v[214:217], v[70:73]
	s_setprio 0
	s_barrier
	s_add_i32 s39, s85, s75
	v_lshl_add_u64 v[218:219], s[46:47], 0, v[134:135]
	s_mov_b32 m0, s39
	ds_read_b128 v[180:183], v170 offset:16384
	ds_read_b128 v[184:187], v170 offset:17408
	ds_read_b128 v[188:191], v170 offset:18432
	ds_read_b128 v[192:195], v170 offset:19456
	ds_read_b128 v[202:205], v170 offset:20480
	ds_read_b128 v[206:209], v170 offset:21504
	ds_read_b128 v[210:213], v170 offset:22528
	ds_read_b128 v[214:217], v170 offset:23552
	global_load_lds_dwordx4 v[218:219], off
	s_add_i32 m0, s39, 0x2000
	s_add_u32 s92, s46, 0x40000
	v_lshl_add_u64 v[220:221], s[46:47], 0, v[130:131]
	s_addc_u32 s93, s47, 0
	s_add_i32 s38, s38, s75
	global_load_lds_dwordx4 v[220:221], off
	v_lshl_add_u64 v[222:223], s[92:93], 0, v[134:135]
	s_mov_b32 m0, s38
	v_lshl_add_u64 v[224:225], s[72:73], 0, v[132:133]
	global_load_lds_dwordx4 v[222:223], off
	v_lshl_add_u64 v[222:223], s[92:93], 0, v[130:131]
	s_add_i32 m0, s38, 0x2000
	s_nop 0
	global_load_lds_dwordx4 v[222:223], off
	v_lshl_add_u64 v[222:223], s[72:73], 0, v[136:137]
	s_mov_b32 m0, s76
	s_nop 0
	global_load_lds_dwordx4 v[222:223], off
	s_mov_b32 m0, s77
	s_nop 0
	global_load_lds_dwordx4 v[224:225], off
	s_waitcnt vmcnt(8)
	s_waitcnt lgkmcnt(0)
	s_barrier
; #define PG8_STAGE(bufoff, gbase, voff) do { _Pragma("unroll") for (int _i = 0; _i < 2; ++_i) \
;         __builtin_amdgcn_global_load_lds((const unsigned*)((const char*)(gbase) + (voff)[_i]), (PG8_LAS unsigned*)(lds + (bufoff) + ldsw + _i * 8192), 16, 0, 0); } while (0)
; #define PG8_LDA(dst, b, h) do { _Pragma("unroll") for (int m = 0; m < 4; ++m) _Pragma("unroll") for (int k = 0; k < 2; ++k) dst[m][k] = *(const PG8_LAS bf16x8*)(lds + PG8_SA(b, h) + aoff + m * 2048 + k * 1024); } while (0)
; #define PG8_LDB(dst, b, h) do { _Pragma("unroll") for (int n = 0; n < 2; ++n) _Pragma("unroll") for (int k = 0; k < 2; ++k) dst[n][k] = *(const PG8_LAS bf16x8*)(lds + PG8_SB(b, h) + boff + n * 2048 + k * 1024); } while (0)
; #define PG8_MMA(ai, bj, At, Bt) do { __builtin_amdgcn_s_setprio(1); _Pragma("unroll") for (int m = 0; m < 4; ++m) _Pragma("unroll") for (int n = 0; n < 2; ++n) _Pragma("unroll") for (int k = 0; k < 2; ++k) \
;         acc[ai][bj][m][n] = __builtin_amdgcn_mfma_f32_16x16x32_bf16(Bt[n][k], At[m][k], acc[ai][bj][m][n], 0, 0, 0); __builtin_amdgcn_s_setprio(0); } while (0)
; #define PG8_WAIT_V(n) asm volatile("s_waitcnt vmcnt(" #n ")" ::: "memory")
; #define PG8_WAIT_L(n) asm volatile("s_waitcnt lgkmcnt(" #n ")" ::: "memory")
; #define PG8_BAR __builtin_amdgcn_s_barrier()
; #define PG8_SCHED __builtin_amdgcn_sched_barrier(0)
; template <class Epi, class Sched, bool ALIGN_EPI = false, bool SP2 = false>
; __device__ __forceinline__ void gemm_phase(PG8_LAS unsigned char* lds, const Gemm g, const Sched& S, const Epi& E) {
;     ...
;             PG8_WAIT_V(8); PG8_WAIT_L(0); PG8_BAR; PG8_MMA(1, 0, At, B0); PG8_MMA(1, 1, At, B1); PG8_BAR; PG8_SCHED;
;             PG8_LDB(B0, 1, 0); PG8_LDB(B1, 1, 1); PG8_SCHED; PG8_LDA(At, 1, 0); PG8_STAGE(PG8_SA(0, 1), a2 + hstep, voffA);
;             PG8_WAIT_V(8); PG8_WAIT_L(0); PG8_BAR; PG8_MMA(0, 0, At, B0); PG8_MMA(0, 1, At, B1); PG8_BAR; PG8_SCHED;
	s_setprio 1
	s_waitcnt lgkmcnt(0)
	v_mfma_f32_16x16x32_bf16 v[58:61], v[142:145], v[180:183], v[58:61]
	v_mfma_f32_16x16x32_bf16 v[58:61], v[146:149], v[184:187], v[58:61]
	v_mfma_f32_16x16x32_bf16 v[50:53], v[158:161], v[180:183], v[50:53]
	v_mfma_f32_16x16x32_bf16 v[50:53], v[162:165], v[184:187], v[50:53]
	v_mfma_f32_16x16x32_bf16 v[62:65], v[150:153], v[180:183], v[62:65]
	v_mfma_f32_16x16x32_bf16 v[62:65], v[154:157], v[184:187], v[62:65]
	v_mfma_f32_16x16x32_bf16 v[54:57], v[172:175], v[180:183], v[54:57]
	v_mfma_f32_16x16x32_bf16 v[54:57], v[176:179], v[184:187], v[54:57]
	v_mfma_f32_16x16x32_bf16 v[42:45], v[142:145], v[188:191], v[42:45]
	v_mfma_f32_16x16x32_bf16 v[42:45], v[146:149], v[192:195], v[42:45]
	v_mfma_f32_16x16x32_bf16 v[34:37], v[158:161], v[188:191], v[34:37]
	v_mfma_f32_16x16x32_bf16 v[34:37], v[162:165], v[192:195], v[34:37]
	v_mfma_f32_16x16x32_bf16 v[46:49], v[150:153], v[188:191], v[46:49]
	v_mfma_f32_16x16x32_bf16 v[46:49], v[154:157], v[192:195], v[46:49]
	v_mfma_f32_16x16x32_bf16 v[38:41], v[172:175], v[188:191], v[38:41]
	v_mfma_f32_16x16x32_bf16 v[38:41], v[176:179], v[192:195], v[38:41]
	v_mfma_f32_16x16x32_bf16 v[26:29], v[142:145], v[202:205], v[26:29]
	v_mfma_f32_16x16x32_bf16 v[26:29], v[146:149], v[206:209], v[26:29]
	v_mfma_f32_16x16x32_bf16 v[18:21], v[158:161], v[202:205], v[18:21]
	v_mfma_f32_16x16x32_bf16 v[18:21], v[162:165], v[206:209], v[18:21]
	v_mfma_f32_16x16x32_bf16 v[30:33], v[150:153], v[202:205], v[30:33]
	v_mfma_f32_16x16x32_bf16 v[30:33], v[154:157], v[206:209], v[30:33]
	v_mfma_f32_16x16x32_bf16 v[22:25], v[172:175], v[202:205], v[22:25]
	v_mfma_f32_16x16x32_bf16 v[22:25], v[176:179], v[206:209], v[22:25]
	v_mfma_f32_16x16x32_bf16 v[10:13], v[142:145], v[210:213], v[10:13]
	v_mfma_f32_16x16x32_bf16 v[10:13], v[146:149], v[214:217], v[10:13]
	v_mfma_f32_16x16x32_bf16 v[2:5], v[158:161], v[210:213], v[2:5]
	v_mfma_f32_16x16x32_bf16 v[2:5], v[162:165], v[214:217], v[2:5]
	v_mfma_f32_16x16x32_bf16 v[14:17], v[150:153], v[210:213], v[14:17]
	v_mfma_f32_16x16x32_bf16 v[14:17], v[154:157], v[214:217], v[14:17]
	v_mfma_f32_16x16x32_bf16 v[6:9], v[172:175], v[210:213], v[6:9]
	v_mfma_f32_16x16x32_bf16 v[6:9], v[176:179], v[214:217], v[6:9]
	s_setprio 0
	s_barrier
	s_add_i32 s38, 0, 0x18000
	v_add_u32_e32 v0, s38, v167
	s_add_i32 s39, 0, 0x1c000
	ds_read_b128 v[142:145], v0
	ds_read_b128 v[146:149], v0 offset:1024
	ds_read_b128 v[150:153], v0 offset:2048
	ds_read_b128 v[154:157], v0 offset:3072
	v_add_u32_e32 v0, s39, v167
	ds_read_b128 v[158:161], v0
	ds_read_b128 v[162:165], v0 offset:1024
	ds_read_b128 v[172:175], v0 offset:2048
	ds_read_b128 v[176:179], v0 offset:3072
	s_add_u32 s72, s72, 0x40000
	s_addc_u32 s73, s73, 0
	s_mov_b32 m0, s78
	v_lshl_add_u64 v[226:227], s[72:73], 0, v[136:137]
	ds_read_b128 v[180:183], v170 offset:32768
	ds_read_b128 v[184:187], v170 offset:33792
	ds_read_b128 v[188:191], v170 offset:34816
	ds_read_b128 v[192:195], v170 offset:35840
	ds_read_b128 v[202:205], v170 offset:36864
	ds_read_b128 v[206:209], v170 offset:37888
	ds_read_b128 v[210:213], v170 offset:38912
	ds_read_b128 v[214:217], v170 offset:39936
	global_load_lds_dwordx4 v[226:227], off
	v_lshl_add_u64 v[226:227], s[72:73], 0, v[132:133]
	s_mov_b32 m0, s79
	s_nop 0
	global_load_lds_dwordx4 v[226:227], off
	s_waitcnt vmcnt(8)
	s_waitcnt lgkmcnt(0)
	s_barrier
	s_setprio 1
	s_waitcnt lgkmcnt(0)
	v_mfma_f32_16x16x32_bf16 v[122:125], v[142:145], v[180:183], v[122:125]
	v_mfma_f32_16x16x32_bf16 v[122:125], v[146:149], v[184:187], v[122:125]
	v_mfma_f32_16x16x32_bf16 v[114:117], v[158:161], v[180:183], v[114:117]
	v_mfma_f32_16x16x32_bf16 v[114:117], v[162:165], v[184:187], v[114:117]
	v_mfma_f32_16x16x32_bf16 v[126:129], v[150:153], v[180:183], v[126:129]
	v_mfma_f32_16x16x32_bf16 v[126:129], v[154:157], v[184:187], v[126:129]
	v_mfma_f32_16x16x32_bf16 v[118:121], v[172:175], v[180:183], v[118:121]
	v_mfma_f32_16x16x32_bf16 v[118:121], v[176:179], v[184:187], v[118:121]
	v_mfma_f32_16x16x32_bf16 v[106:109], v[142:145], v[188:191], v[106:109]
	v_mfma_f32_16x16x32_bf16 v[106:109], v[146:149], v[192:195], v[106:109]
	v_mfma_f32_16x16x32_bf16 v[98:101], v[158:161], v[188:191], v[98:101]
	v_mfma_f32_16x16x32_bf16 v[98:101], v[162:165], v[192:195], v[98:101]
	v_mfma_f32_16x16x32_bf16 v[110:113], v[150:153], v[188:191], v[110:113]
	v_mfma_f32_16x16x32_bf16 v[110:113], v[154:157], v[192:195], v[110:113]
	v_mfma_f32_16x16x32_bf16 v[102:105], v[172:175], v[188:191], v[102:105]
	v_mfma_f32_16x16x32_bf16 v[102:105], v[176:179], v[192:195], v[102:105]
	v_mfma_f32_16x16x32_bf16 v[90:93], v[142:145], v[202:205], v[90:93]
	v_mfma_f32_16x16x32_bf16 v[90:93], v[146:149], v[206:209], v[90:93]
	v_mfma_f32_16x16x32_bf16 v[82:85], v[158:161], v[202:205], v[82:85]
	v_mfma_f32_16x16x32_bf16 v[82:85], v[162:165], v[206:209], v[82:85]
	v_mfma_f32_16x16x32_bf16 v[94:97], v[150:153], v[202:205], v[94:97]
	v_mfma_f32_16x16x32_bf16 v[94:97], v[154:157], v[206:209], v[94:97]
	v_mfma_f32_16x16x32_bf16 v[86:89], v[172:175], v[202:205], v[86:89]
	v_mfma_f32_16x16x32_bf16 v[86:89], v[176:179], v[206:209], v[86:89]
	v_mfma_f32_16x16x32_bf16 v[74:77], v[142:145], v[210:213], v[74:77]
	v_mfma_f32_16x16x32_bf16 v[74:77], v[146:149], v[214:217], v[74:77]
	v_mfma_f32_16x16x32_bf16 v[66:69], v[158:161], v[210:213], v[66:69]
	v_mfma_f32_16x16x32_bf16 v[66:69], v[162:165], v[214:217], v[66:69]
	v_mfma_f32_16x16x32_bf16 v[78:81], v[150:153], v[210:213], v[78:81]
	v_mfma_f32_16x16x32_bf16 v[78:81], v[154:157], v[214:217], v[78:81]
	v_mfma_f32_16x16x32_bf16 v[70:73], v[172:175], v[210:213], v[70:73]
	v_mfma_f32_16x16x32_bf16 v[70:73], v[176:179], v[214:217], v[70:73]
	s_setprio 0
	s_barrier
; #define PG8_STAGE(bufoff, gbase, voff) do { _Pragma("unroll") for (int _i = 0; _i < 2; ++_i) \
;         __builtin_amdgcn_global_load_lds((const unsigned*)((const char*)(gbase) + (voff)[_i]), (PG8_LAS unsigned*)(lds + (bufoff) + ldsw + _i * 8192), 16, 0, 0); } while (0)
; #define PG8_LDA(dst, b, h) do { _Pragma("unroll") for (int m = 0; m < 4; ++m) _Pragma("unroll") for (int k = 0; k < 2; ++k) dst[m][k] = *(const PG8_LAS bf16x8*)(lds + PG8_SA(b, h) + aoff + m * 2048 + k * 1024); } while (0)
; #define PG8_MMA(ai, bj, At, Bt) do { __builtin_amdgcn_s_setprio(1); _Pragma("unroll") for (int m = 0; m < 4; ++m) _Pragma("unroll") for (int n = 0; n < 2; ++n) _Pragma("unroll") for (int k = 0; k < 2; ++k) \
;         acc[ai][bj][m][n] = __builtin_amdgcn_mfma_f32_16x16x32_bf16(Bt[n][k], At[m][k], acc[ai][bj][m][n], 0, 0, 0); __builtin_amdgcn_s_setprio(0); } while (0)
; #define PG8_WAIT_V(n) asm volatile("s_waitcnt vmcnt(" #n ")" ::: "memory")
; #define PG8_WAIT_L(n) asm volatile("s_waitcnt lgkmcnt(" #n ")" ::: "memory")
; #define PG8_BAR __builtin_amdgcn_s_barrier()
; #define PG8_SCHED __builtin_amdgcn_sched_barrier(0)
; template <class Epi, class Sched, bool ALIGN_EPI = false, bool SP2 = false>
; __device__ __forceinline__ void gemm_phase(PG8_LAS unsigned char* lds, const Gemm g, const Sched& S, const Epi& E) {
;     ...
;             PG8_LDA(At, 1, 1); PG8_STAGE(PG8_SB(1, 0), b3, voffB); PG8_STAGE(PG8_SB(1, 1), b3 + hstep, voffB); PG8_STAGE(PG8_SA(1, 0), a3, voffA);
;             PG8_WAIT_V(8); PG8_WAIT_L(0); PG8_BAR; PG8_MMA(1, 0, At, B0); PG8_MMA(1, 1, At, B1); PG8_BAR; PG8_SCHED;
;     ...
;         if constexpr (ALIGN_EPI) { if (wr == 0) PG8_BAR; }
	s_add_i32 s38, s38, s75
	v_lshl_add_u64 v[218:219], v[218:219], 0, s[30:31]
	s_mov_b32 m0, s38
	ds_read_b128 v[180:183], v170 offset:49152
	ds_read_b128 v[184:187], v170 offset:50176
	ds_read_b128 v[188:191], v170 offset:51200
	ds_read_b128 v[192:195], v170 offset:52224
	ds_read_b128 v[202:205], v170 offset:53248
	ds_read_b128 v[206:209], v170 offset:54272
	ds_read_b128 v[210:213], v170 offset:55296
	ds_read_b128 v[214:217], v170 offset:56320
	global_load_lds_dwordx4 v[218:219], off
	s_add_i32 m0, s38, 0x2000
	s_add_u32 s46, s46, 0x40080
	v_lshl_add_u64 v[218:219], v[220:221], 0, s[30:31]
	s_addc_u32 s47, s47, 0
	s_add_i32 s38, s39, s75
	global_load_lds_dwordx4 v[218:219], off
	v_lshl_add_u64 v[218:219], s[46:47], 0, v[134:135]
	s_mov_b32 m0, s38
	s_nop 0
	global_load_lds_dwordx4 v[218:219], off
	v_lshl_add_u64 v[218:219], s[46:47], 0, v[130:131]
	s_add_i32 m0, s38, 0x2000
	s_nop 0
	global_load_lds_dwordx4 v[218:219], off
	v_lshl_add_u64 v[218:219], v[222:223], 0, s[30:31]
	s_mov_b32 m0, s80
	s_nop 0
	global_load_lds_dwordx4 v[218:219], off
	v_lshl_add_u64 v[218:219], v[224:225], 0, s[30:31]
	s_mov_b32 m0, s81
	s_nop 0
	global_load_lds_dwordx4 v[218:219], off
	s_waitcnt vmcnt(8)
	s_waitcnt lgkmcnt(0)
	s_barrier
	s_setprio 1
	s_waitcnt lgkmcnt(0)
	v_mfma_f32_16x16x32_bf16 v[58:61], v[142:145], v[180:183], v[58:61]
	v_mfma_f32_16x16x32_bf16 v[58:61], v[146:149], v[184:187], v[58:61]
	v_mfma_f32_16x16x32_bf16 v[50:53], v[158:161], v[180:183], v[50:53]
	v_mfma_f32_16x16x32_bf16 v[50:53], v[162:165], v[184:187], v[50:53]
	v_mfma_f32_16x16x32_bf16 v[62:65], v[150:153], v[180:183], v[62:65]
	v_mfma_f32_16x16x32_bf16 v[62:65], v[154:157], v[184:187], v[62:65]
	v_mfma_f32_16x16x32_bf16 v[54:57], v[172:175], v[180:183], v[54:57]
	v_mfma_f32_16x16x32_bf16 v[54:57], v[176:179], v[184:187], v[54:57]
	v_mfma_f32_16x16x32_bf16 v[42:45], v[142:145], v[188:191], v[42:45]
	v_mfma_f32_16x16x32_bf16 v[42:45], v[146:149], v[192:195], v[42:45]
	v_mfma_f32_16x16x32_bf16 v[34:37], v[158:161], v[188:191], v[34:37]
	v_mfma_f32_16x16x32_bf16 v[34:37], v[162:165], v[192:195], v[34:37]
	v_mfma_f32_16x16x32_bf16 v[46:49], v[150:153], v[188:191], v[46:49]
	v_mfma_f32_16x16x32_bf16 v[46:49], v[154:157], v[192:195], v[46:49]
	v_mfma_f32_16x16x32_bf16 v[38:41], v[172:175], v[188:191], v[38:41]
	v_mfma_f32_16x16x32_bf16 v[38:41], v[176:179], v[192:195], v[38:41]
	v_mfma_f32_16x16x32_bf16 v[26:29], v[142:145], v[202:205], v[26:29]
	v_mfma_f32_16x16x32_bf16 v[26:29], v[146:149], v[206:209], v[26:29]
	v_mfma_f32_16x16x32_bf16 v[18:21], v[158:161], v[202:205], v[18:21]
	v_mfma_f32_16x16x32_bf16 v[18:21], v[162:165], v[206:209], v[18:21]
	v_mfma_f32_16x16x32_bf16 v[30:33], v[150:153], v[202:205], v[30:33]
	v_mfma_f32_16x16x32_bf16 v[30:33], v[154:157], v[206:209], v[30:33]
	v_mfma_f32_16x16x32_bf16 v[22:25], v[172:175], v[202:205], v[22:25]
	v_mfma_f32_16x16x32_bf16 v[22:25], v[176:179], v[206:209], v[22:25]
	v_mfma_f32_16x16x32_bf16 v[10:13], v[142:145], v[210:213], v[10:13]
	v_mfma_f32_16x16x32_bf16 v[10:13], v[146:149], v[214:217], v[10:13]
	v_mfma_f32_16x16x32_bf16 v[2:5], v[158:161], v[210:213], v[2:5]
	v_mfma_f32_16x16x32_bf16 v[2:5], v[162:165], v[214:217], v[2:5]
	v_mfma_f32_16x16x32_bf16 v[14:17], v[150:153], v[210:213], v[14:17]
	v_mfma_f32_16x16x32_bf16 v[14:17], v[154:157], v[214:217], v[14:17]
	v_mfma_f32_16x16x32_bf16 v[6:9], v[172:175], v[210:213], v[6:9]
	v_mfma_f32_16x16x32_bf16 v[6:9], v[176:179], v[214:217], v[6:9]
	s_setprio 0
	s_barrier
	s_add_i32 s84, s84, 2
	s_add_u32 s48, s48, 0x100
	s_addc_u32 s49, s49, 0
	s_add_u32 s53, s53, 0x100
	s_addc_u32 s69, s69, 0
	s_cmp_gt_u32 s84, 13
	s_cbranch_scc0 .LBB0_408
	s_and_b64 vcc, exec, s[64:65]
	s_cbranch_vccz .LBB0_411
	s_barrier
